# GEMM K-loops: LDS-DMA loads use SGPR-base addressing (no VALU address adds in load segments), on top of P0 item pipeline
# speedup vs baseline: 1.0050x; 1.0050x over previous
.LBB0_446:
	ds_read_b128 v[148:151], v165
	ds_read_b128 v[174:177], v165 offset:1024
	ds_read_b128 v[180:183], v165 offset:2048
	ds_read_b128 v[184:187], v165 offset:3072
	ds_read_b128 v[188:191], v169
	ds_read_b128 v[192:195], v169 offset:1024
	ds_read_b128 v[196:199], v169 offset:2048
	ds_read_b128 v[200:203], v169 offset:3072
	s_add_u32 s50, s4, 0xfff00080
	s_addc_u32 s51, s5, -1
	s_cmp_eq_u32 s68, 60
	s_cselect_b32 s53, s3, s51
	s_cselect_b32 s52, s8, s50
	s_cselect_b32 s51, s39, s65
	s_cselect_b32 s50, s45, s63
	s_add_i32 m0, s7, 0xc000
	ds_read_b128 v[204:207], v173
	ds_read_b128 v[208:211], v173 offset:1024
	ds_read_b128 v[212:215], v173 offset:2048
	ds_read_b128 v[216:219], v173 offset:3072
	ds_read_b128 v[220:223], v173 offset:4096
	ds_read_b128 v[224:227], v173 offset:5120
	ds_read_b128 v[228:231], v173 offset:6144
	ds_read_b128 v[236:239], v173 offset:7168
	global_load_lds_dwordx4 v140, s[4:5]
	s_add_i32 m0, s7, 0xe000
	s_nop 0
	global_load_lds_dwordx4 v142, s[4:5]
	s_waitcnt vmcnt(8)
	s_waitcnt lgkmcnt(0)
	s_barrier
	s_setprio 1
	s_waitcnt lgkmcnt(0)
	v_mfma_f32_16x16x32_bf16 v[126:129], v[148:151], v[204:207], v[126:129]
	v_mfma_f32_16x16x32_bf16 v[122:125], v[180:183], v[204:207], v[122:125]
	v_mfma_f32_16x16x32_bf16 v[110:113], v[148:151], v[212:215], v[110:113]
	v_mfma_f32_16x16x32_bf16 v[106:109], v[180:183], v[212:215], v[106:109]
	v_mfma_f32_16x16x32_bf16 v[94:97], v[148:151], v[220:223], v[94:97]
	v_mfma_f32_16x16x32_bf16 v[90:93], v[180:183], v[220:223], v[90:93]
	v_mfma_f32_16x16x32_bf16 v[78:81], v[148:151], v[228:231], v[78:81]
	v_mfma_f32_16x16x32_bf16 v[74:77], v[180:183], v[228:231], v[74:77]
	v_mfma_f32_16x16x32_bf16 v[126:129], v[174:177], v[208:211], v[126:129]
	v_mfma_f32_16x16x32_bf16 v[122:125], v[184:187], v[208:211], v[122:125]
	v_mfma_f32_16x16x32_bf16 v[110:113], v[174:177], v[216:219], v[110:113]
	v_mfma_f32_16x16x32_bf16 v[106:109], v[184:187], v[216:219], v[106:109]
	v_mfma_f32_16x16x32_bf16 v[94:97], v[174:177], v[224:227], v[94:97]
	v_mfma_f32_16x16x32_bf16 v[90:93], v[184:187], v[224:227], v[90:93]
	v_mfma_f32_16x16x32_bf16 v[78:81], v[174:177], v[236:239], v[78:81]
	v_mfma_f32_16x16x32_bf16 v[74:77], v[184:187], v[236:239], v[74:77]
	s_setprio 0
	s_setprio 1
	v_mfma_f32_16x16x32_bf16 v[118:121], v[188:191], v[204:207], v[118:121]
	v_mfma_f32_16x16x32_bf16 v[114:117], v[196:199], v[204:207], v[114:117]
	v_mfma_f32_16x16x32_bf16 v[102:105], v[188:191], v[212:215], v[102:105]
	v_mfma_f32_16x16x32_bf16 v[98:101], v[196:199], v[212:215], v[98:101]
	v_mfma_f32_16x16x32_bf16 v[86:89], v[188:191], v[220:223], v[86:89]
	v_mfma_f32_16x16x32_bf16 v[82:85], v[196:199], v[220:223], v[82:85]
	v_mfma_f32_16x16x32_bf16 v[70:73], v[188:191], v[228:231], v[70:73]
	v_mfma_f32_16x16x32_bf16 v[66:69], v[196:199], v[228:231], v[66:69]
	v_mfma_f32_16x16x32_bf16 v[118:121], v[192:195], v[208:211], v[118:121]
	v_mfma_f32_16x16x32_bf16 v[114:117], v[200:203], v[208:211], v[114:117]
	v_mfma_f32_16x16x32_bf16 v[102:105], v[192:195], v[216:219], v[102:105]
	v_mfma_f32_16x16x32_bf16 v[98:101], v[200:203], v[216:219], v[98:101]
	v_mfma_f32_16x16x32_bf16 v[86:89], v[192:195], v[224:227], v[86:89]
	v_mfma_f32_16x16x32_bf16 v[82:85], v[200:203], v[224:227], v[82:85]
	v_mfma_f32_16x16x32_bf16 v[70:73], v[192:195], v[236:239], v[70:73]
	v_mfma_f32_16x16x32_bf16 v[66:69], v[200:203], v[236:239], v[66:69]
	s_setprio 0
	s_barrier
	s_add_i32 s69, s59, s35
	s_add_u32 s98, s50, s16
	s_addc_u32 s99, s51, s17
	s_mov_b32 m0, s69
	ds_read_b128 v[204:207], v173 offset:16384
	ds_read_b128 v[208:211], v173 offset:17408
	ds_read_b128 v[212:215], v173 offset:18432
	ds_read_b128 v[216:219], v173 offset:19456
	ds_read_b128 v[220:223], v173 offset:20480
	ds_read_b128 v[224:227], v173 offset:21504
	ds_read_b128 v[228:231], v173 offset:22528
	ds_read_b128 v[236:239], v173 offset:23552
	global_load_lds_dwordx4 v132, s[50:51]
	s_add_i32 m0, s69, 0x2000
	s_add_u32 s70, s50, 0x100000
	s_addc_u32 s71, s51, 0
	s_add_i32 s69, s60, s35
	global_load_lds_dwordx4 v136, s[50:51]
	s_mov_b32 m0, s69
	s_nop 0
	global_load_lds_dwordx4 v132, s[70:71]
	s_add_i32 m0, s69, 0x2000
	s_nop 0
	global_load_lds_dwordx4 v136, s[70:71]
	s_add_u32 s100, s52, s16
	s_addc_u32 s101, s53, s17
	s_mov_b32 m0, s7
	s_nop 0
	global_load_lds_dwordx4 v130, s[52:53]
	s_mov_b32 m0, s37
	s_nop 0
	global_load_lds_dwordx4 v134, s[52:53]
	s_waitcnt vmcnt(8)
	s_waitcnt lgkmcnt(0)
	s_barrier
	s_setprio 1
	s_waitcnt lgkmcnt(0)
	v_mfma_f32_16x16x32_bf16 v[62:65], v[148:151], v[204:207], v[62:65]
	v_mfma_f32_16x16x32_bf16 v[58:61], v[180:183], v[204:207], v[58:61]
	v_mfma_f32_16x16x32_bf16 v[46:49], v[148:151], v[212:215], v[46:49]
	v_mfma_f32_16x16x32_bf16 v[42:45], v[180:183], v[212:215], v[42:45]
	v_mfma_f32_16x16x32_bf16 v[30:33], v[148:151], v[220:223], v[30:33]
	v_mfma_f32_16x16x32_bf16 v[26:29], v[180:183], v[220:223], v[26:29]
	v_mfma_f32_16x16x32_bf16 v[14:17], v[148:151], v[228:231], v[14:17]
	v_mfma_f32_16x16x32_bf16 v[10:13], v[180:183], v[228:231], v[10:13]
	v_mfma_f32_16x16x32_bf16 v[62:65], v[174:177], v[208:211], v[62:65]
	v_mfma_f32_16x16x32_bf16 v[58:61], v[184:187], v[208:211], v[58:61]
	v_mfma_f32_16x16x32_bf16 v[46:49], v[174:177], v[216:219], v[46:49]
	v_mfma_f32_16x16x32_bf16 v[42:45], v[184:187], v[216:219], v[42:45]
	v_mfma_f32_16x16x32_bf16 v[30:33], v[174:177], v[224:227], v[30:33]
	v_mfma_f32_16x16x32_bf16 v[26:29], v[184:187], v[224:227], v[26:29]
	v_mfma_f32_16x16x32_bf16 v[14:17], v[174:177], v[236:239], v[14:17]
	v_mfma_f32_16x16x32_bf16 v[10:13], v[184:187], v[236:239], v[10:13]
	s_setprio 0
	s_setprio 1
	v_mfma_f32_16x16x32_bf16 v[54:57], v[188:191], v[204:207], v[54:57]
	v_mfma_f32_16x16x32_bf16 v[50:53], v[196:199], v[204:207], v[50:53]
	v_mfma_f32_16x16x32_bf16 v[38:41], v[188:191], v[212:215], v[38:41]
	v_mfma_f32_16x16x32_bf16 v[34:37], v[196:199], v[212:215], v[34:37]
	v_mfma_f32_16x16x32_bf16 v[22:25], v[188:191], v[220:223], v[22:25]
	v_mfma_f32_16x16x32_bf16 v[18:21], v[196:199], v[220:223], v[18:21]
	v_mfma_f32_16x16x32_bf16 v[6:9], v[188:191], v[228:231], v[6:9]
	v_mfma_f32_16x16x32_bf16 v[2:5], v[196:199], v[228:231], v[2:5]
	v_mfma_f32_16x16x32_bf16 v[54:57], v[192:195], v[208:211], v[54:57]
	v_mfma_f32_16x16x32_bf16 v[50:53], v[200:203], v[208:211], v[50:53]
	v_mfma_f32_16x16x32_bf16 v[38:41], v[192:195], v[216:219], v[38:41]
	v_mfma_f32_16x16x32_bf16 v[34:37], v[200:203], v[216:219], v[34:37]
	v_mfma_f32_16x16x32_bf16 v[22:25], v[192:195], v[224:227], v[22:25]
	v_mfma_f32_16x16x32_bf16 v[18:21], v[200:203], v[224:227], v[18:21]
	v_mfma_f32_16x16x32_bf16 v[6:9], v[192:195], v[236:239], v[6:9]
	v_mfma_f32_16x16x32_bf16 v[2:5], v[200:203], v[236:239], v[2:5]
	s_setprio 0
	s_barrier
	s_add_i32 s69, 0, 0x18000
	v_add_u32_e32 v139, s69, v161
	s_add_i32 s70, 0, 0x1c000
	ds_read_b128 v[148:151], v139
	ds_read_b128 v[174:177], v139 offset:1024
	ds_read_b128 v[180:183], v139 offset:2048
	ds_read_b128 v[184:187], v139 offset:3072
	v_add_u32_e32 v139, s70, v161
	ds_read_b128 v[188:191], v139
	ds_read_b128 v[192:195], v139 offset:1024
	ds_read_b128 v[196:199], v139 offset:2048
	ds_read_b128 v[200:203], v139 offset:3072
	s_add_u32 s52, s52, 0x100000
	s_addc_u32 s53, s53, 0
	s_mov_b32 m0, s41
	ds_read_b128 v[204:207], v173 offset:32768
	ds_read_b128 v[208:211], v173 offset:33792
	ds_read_b128 v[212:215], v173 offset:34816
	ds_read_b128 v[216:219], v173 offset:35840
	ds_read_b128 v[220:223], v173 offset:36864
	ds_read_b128 v[224:227], v173 offset:37888
	ds_read_b128 v[228:231], v173 offset:38912
	ds_read_b128 v[236:239], v173 offset:39936
	global_load_lds_dwordx4 v130, s[52:53]
	s_mov_b32 m0, s43
	s_nop 0
	global_load_lds_dwordx4 v134, s[52:53]
	s_waitcnt vmcnt(8)
	s_waitcnt lgkmcnt(0)
	s_barrier
	s_setprio 1
	s_waitcnt lgkmcnt(0)
	v_mfma_f32_16x16x32_bf16 v[126:129], v[148:151], v[204:207], v[126:129]
	v_mfma_f32_16x16x32_bf16 v[122:125], v[180:183], v[204:207], v[122:125]
	v_mfma_f32_16x16x32_bf16 v[110:113], v[148:151], v[212:215], v[110:113]
	v_mfma_f32_16x16x32_bf16 v[106:109], v[180:183], v[212:215], v[106:109]
	v_mfma_f32_16x16x32_bf16 v[94:97], v[148:151], v[220:223], v[94:97]
	v_mfma_f32_16x16x32_bf16 v[90:93], v[180:183], v[220:223], v[90:93]
	v_mfma_f32_16x16x32_bf16 v[78:81], v[148:151], v[228:231], v[78:81]
	v_mfma_f32_16x16x32_bf16 v[74:77], v[180:183], v[228:231], v[74:77]
	v_mfma_f32_16x16x32_bf16 v[126:129], v[174:177], v[208:211], v[126:129]
	v_mfma_f32_16x16x32_bf16 v[122:125], v[184:187], v[208:211], v[122:125]
	v_mfma_f32_16x16x32_bf16 v[110:113], v[174:177], v[216:219], v[110:113]
	v_mfma_f32_16x16x32_bf16 v[106:109], v[184:187], v[216:219], v[106:109]
	v_mfma_f32_16x16x32_bf16 v[94:97], v[174:177], v[224:227], v[94:97]
	v_mfma_f32_16x16x32_bf16 v[90:93], v[184:187], v[224:227], v[90:93]
	v_mfma_f32_16x16x32_bf16 v[78:81], v[174:177], v[236:239], v[78:81]
	v_mfma_f32_16x16x32_bf16 v[74:77], v[184:187], v[236:239], v[74:77]
	s_setprio 0
	s_setprio 1
	v_mfma_f32_16x16x32_bf16 v[118:121], v[188:191], v[204:207], v[118:121]
	v_mfma_f32_16x16x32_bf16 v[114:117], v[196:199], v[204:207], v[114:117]
	v_mfma_f32_16x16x32_bf16 v[102:105], v[188:191], v[212:215], v[102:105]
	v_mfma_f32_16x16x32_bf16 v[98:101], v[196:199], v[212:215], v[98:101]
	v_mfma_f32_16x16x32_bf16 v[86:89], v[188:191], v[220:223], v[86:89]
	v_mfma_f32_16x16x32_bf16 v[82:85], v[196:199], v[220:223], v[82:85]
	v_mfma_f32_16x16x32_bf16 v[70:73], v[188:191], v[228:231], v[70:73]
	v_mfma_f32_16x16x32_bf16 v[66:69], v[196:199], v[228:231], v[66:69]
	v_mfma_f32_16x16x32_bf16 v[118:121], v[192:195], v[208:211], v[118:121]
	v_mfma_f32_16x16x32_bf16 v[114:117], v[200:203], v[208:211], v[114:117]
	v_mfma_f32_16x16x32_bf16 v[102:105], v[192:195], v[216:219], v[102:105]
	v_mfma_f32_16x16x32_bf16 v[98:101], v[200:203], v[216:219], v[98:101]
	v_mfma_f32_16x16x32_bf16 v[86:89], v[192:195], v[224:227], v[86:89]
	v_mfma_f32_16x16x32_bf16 v[82:85], v[200:203], v[224:227], v[82:85]
	v_mfma_f32_16x16x32_bf16 v[70:73], v[192:195], v[236:239], v[70:73]
	v_mfma_f32_16x16x32_bf16 v[66:69], v[200:203], v[236:239], v[66:69]
	s_setprio 0
	s_barrier
	s_add_i32 s52, s69, s35
	s_mov_b32 m0, s52
	ds_read_b128 v[204:207], v173 offset:49152
	ds_read_b128 v[208:211], v173 offset:50176
	ds_read_b128 v[212:215], v173 offset:51200
	ds_read_b128 v[216:219], v173 offset:52224
	ds_read_b128 v[220:223], v173 offset:53248
	ds_read_b128 v[224:227], v173 offset:54272
	ds_read_b128 v[228:231], v173 offset:55296
	ds_read_b128 v[236:239], v173 offset:56320
	global_load_lds_dwordx4 v132, s[98:99]
	s_add_i32 m0, s52, 0x2000
	s_add_u32 s50, s50, 0x100080
	s_addc_u32 s51, s51, 0
	s_add_i32 s52, s70, s35
	global_load_lds_dwordx4 v136, s[98:99]
	s_mov_b32 m0, s52
	s_nop 0
	global_load_lds_dwordx4 v132, s[50:51]
	s_add_i32 m0, s52, 0x2000
	s_nop 0
	global_load_lds_dwordx4 v136, s[50:51]
	s_mov_b32 m0, s57
	s_nop 0
	global_load_lds_dwordx4 v130, s[100:101]
	s_mov_b32 m0, s58
	s_nop 0
	global_load_lds_dwordx4 v134, s[100:101]
	s_waitcnt vmcnt(8)
	s_waitcnt lgkmcnt(0)
	s_barrier
	s_setprio 1
	s_waitcnt lgkmcnt(0)
	v_mfma_f32_16x16x32_bf16 v[62:65], v[148:151], v[204:207], v[62:65]
	v_mfma_f32_16x16x32_bf16 v[58:61], v[180:183], v[204:207], v[58:61]
	v_mfma_f32_16x16x32_bf16 v[46:49], v[148:151], v[212:215], v[46:49]
	v_mfma_f32_16x16x32_bf16 v[42:45], v[180:183], v[212:215], v[42:45]
	v_mfma_f32_16x16x32_bf16 v[30:33], v[148:151], v[220:223], v[30:33]
	v_mfma_f32_16x16x32_bf16 v[26:29], v[180:183], v[220:223], v[26:29]
	v_mfma_f32_16x16x32_bf16 v[14:17], v[148:151], v[228:231], v[14:17]
	v_mfma_f32_16x16x32_bf16 v[10:13], v[180:183], v[228:231], v[10:13]
	v_mfma_f32_16x16x32_bf16 v[62:65], v[174:177], v[208:211], v[62:65]
	v_mfma_f32_16x16x32_bf16 v[58:61], v[184:187], v[208:211], v[58:61]
	v_mfma_f32_16x16x32_bf16 v[46:49], v[174:177], v[216:219], v[46:49]
	v_mfma_f32_16x16x32_bf16 v[42:45], v[184:187], v[216:219], v[42:45]
	v_mfma_f32_16x16x32_bf16 v[30:33], v[174:177], v[224:227], v[30:33]
	v_mfma_f32_16x16x32_bf16 v[26:29], v[184:187], v[224:227], v[26:29]
	v_mfma_f32_16x16x32_bf16 v[14:17], v[174:177], v[236:239], v[14:17]
	v_mfma_f32_16x16x32_bf16 v[10:13], v[184:187], v[236:239], v[10:13]
	s_setprio 0
	s_setprio 1
	v_mfma_f32_16x16x32_bf16 v[54:57], v[188:191], v[204:207], v[54:57]
	v_mfma_f32_16x16x32_bf16 v[50:53], v[196:199], v[204:207], v[50:53]
	v_mfma_f32_16x16x32_bf16 v[38:41], v[188:191], v[212:215], v[38:41]
	v_mfma_f32_16x16x32_bf16 v[34:37], v[196:199], v[212:215], v[34:37]
	v_mfma_f32_16x16x32_bf16 v[22:25], v[188:191], v[220:223], v[22:25]
	v_mfma_f32_16x16x32_bf16 v[18:21], v[196:199], v[220:223], v[18:21]
	v_mfma_f32_16x16x32_bf16 v[6:9], v[188:191], v[228:231], v[6:9]
	v_mfma_f32_16x16x32_bf16 v[2:5], v[196:199], v[228:231], v[2:5]
	v_mfma_f32_16x16x32_bf16 v[54:57], v[192:195], v[208:211], v[54:57]
	v_mfma_f32_16x16x32_bf16 v[50:53], v[200:203], v[208:211], v[50:53]
	v_mfma_f32_16x16x32_bf16 v[38:41], v[192:195], v[216:219], v[38:41]
	v_mfma_f32_16x16x32_bf16 v[34:37], v[200:203], v[216:219], v[34:37]
	v_mfma_f32_16x16x32_bf16 v[22:25], v[192:195], v[224:227], v[22:25]
	v_mfma_f32_16x16x32_bf16 v[18:21], v[200:203], v[224:227], v[18:21]
	v_mfma_f32_16x16x32_bf16 v[6:9], v[192:195], v[236:239], v[6:9]
	v_mfma_f32_16x16x32_bf16 v[2:5], v[200:203], v[236:239], v[2:5]
	s_setprio 0
	s_barrier
	s_add_i32 s68, s68, 2
	s_add_u32 s4, s4, 0x100
	s_addc_u32 s5, s5, 0
	s_add_u32 s63, s63, 0x100
	s_addc_u32 s65, s65, 0
	s_cmp_gt_u32 s68, 61
	s_cbranch_scc0 .LBB0_446
	s_and_b64 vcc, exec, s[20:21]
	s_cbranch_vccz .LBB0_449
	s_barrier

.LBB0_668:
	ds_read_b128 v[154:157], v151
	ds_read_b128 v[158:161], v151 offset:1024
	ds_read_b128 v[162:165], v151 offset:2048
	ds_read_b128 v[166:169], v151 offset:3072
	ds_read_b128 v[170:173], v152
	ds_read_b128 v[174:177], v152 offset:1024
	ds_read_b128 v[178:181], v152 offset:2048
	ds_read_b128 v[182:185], v152 offset:3072
	s_add_u32 s36, s34, 0xfff00080
	s_addc_u32 s37, s35, -1
	s_cmp_eq_u32 s68, 60
	s_cselect_b32 s39, s25, s37
	s_cselect_b32 s38, s61, s36
	s_cselect_b32 s37, s23, s65
	s_cselect_b32 s36, s62, s63
	s_add_i32 m0, s31, 0xc000
	ds_read_b128 v[186:189], v153
	ds_read_b128 v[190:193], v153 offset:1024
	ds_read_b128 v[194:197], v153 offset:2048
	ds_read_b128 v[198:201], v153 offset:3072
	ds_read_b128 v[202:205], v153 offset:4096
	ds_read_b128 v[206:209], v153 offset:5120
	ds_read_b128 v[210:213], v153 offset:6144
	ds_read_b128 v[214:217], v153 offset:7168
	global_load_lds_dwordx4 v140, s[34:35]
	s_add_i32 m0, s31, 0xe000
	s_nop 0
	global_load_lds_dwordx4 v142, s[34:35]
	s_waitcnt vmcnt(8)
	s_waitcnt lgkmcnt(0)
	s_barrier
	s_setprio 1
	s_waitcnt lgkmcnt(0)
	v_mfma_f32_16x16x32_bf16 v[126:129], v[154:157], v[186:189], v[126:129]
	v_mfma_f32_16x16x32_bf16 v[122:125], v[162:165], v[186:189], v[122:125]
	v_mfma_f32_16x16x32_bf16 v[114:117], v[154:157], v[194:197], v[114:117]
	v_mfma_f32_16x16x32_bf16 v[106:109], v[162:165], v[194:197], v[106:109]
	v_mfma_f32_16x16x32_bf16 v[98:101], v[154:157], v[202:205], v[98:101]
	v_mfma_f32_16x16x32_bf16 v[90:93], v[162:165], v[202:205], v[90:93]
	v_mfma_f32_16x16x32_bf16 v[82:85], v[154:157], v[210:213], v[82:85]
	v_mfma_f32_16x16x32_bf16 v[74:77], v[162:165], v[210:213], v[74:77]
	v_mfma_f32_16x16x32_bf16 v[126:129], v[158:161], v[190:193], v[126:129]
	v_mfma_f32_16x16x32_bf16 v[122:125], v[166:169], v[190:193], v[122:125]
	v_mfma_f32_16x16x32_bf16 v[114:117], v[158:161], v[198:201], v[114:117]
	v_mfma_f32_16x16x32_bf16 v[106:109], v[166:169], v[198:201], v[106:109]
	v_mfma_f32_16x16x32_bf16 v[98:101], v[158:161], v[206:209], v[98:101]
	v_mfma_f32_16x16x32_bf16 v[90:93], v[166:169], v[206:209], v[90:93]
	v_mfma_f32_16x16x32_bf16 v[82:85], v[158:161], v[214:217], v[82:85]
	v_mfma_f32_16x16x32_bf16 v[74:77], v[166:169], v[214:217], v[74:77]
	s_setprio 0
	s_setprio 1
	v_mfma_f32_16x16x32_bf16 v[118:121], v[170:173], v[186:189], v[118:121]
	v_mfma_f32_16x16x32_bf16 v[110:113], v[178:181], v[186:189], v[110:113]
	v_mfma_f32_16x16x32_bf16 v[102:105], v[170:173], v[194:197], v[102:105]
	v_mfma_f32_16x16x32_bf16 v[94:97], v[178:181], v[194:197], v[94:97]
	v_mfma_f32_16x16x32_bf16 v[86:89], v[170:173], v[202:205], v[86:89]
	v_mfma_f32_16x16x32_bf16 v[78:81], v[178:181], v[202:205], v[78:81]
	v_mfma_f32_16x16x32_bf16 v[70:73], v[170:173], v[210:213], v[70:73]
	v_mfma_f32_16x16x32_bf16 v[66:69], v[178:181], v[210:213], v[66:69]
	v_mfma_f32_16x16x32_bf16 v[118:121], v[174:177], v[190:193], v[118:121]
	v_mfma_f32_16x16x32_bf16 v[110:113], v[182:185], v[190:193], v[110:113]
	v_mfma_f32_16x16x32_bf16 v[102:105], v[174:177], v[198:201], v[102:105]
	v_mfma_f32_16x16x32_bf16 v[94:97], v[182:185], v[198:201], v[94:97]
	v_mfma_f32_16x16x32_bf16 v[86:89], v[174:177], v[206:209], v[86:89]
	v_mfma_f32_16x16x32_bf16 v[78:81], v[182:185], v[206:209], v[78:81]
	v_mfma_f32_16x16x32_bf16 v[70:73], v[174:177], v[214:217], v[70:73]
	v_mfma_f32_16x16x32_bf16 v[66:69], v[182:185], v[214:217], v[66:69]
	s_setprio 0
	s_barrier
	s_add_i32 s69, s54, s47
	s_add_u32 s98, s36, s8
	s_addc_u32 s99, s37, s9
	s_mov_b32 m0, s69
	ds_read_b128 v[186:189], v153 offset:16384
	ds_read_b128 v[190:193], v153 offset:17408
	ds_read_b128 v[194:197], v153 offset:18432
	ds_read_b128 v[198:201], v153 offset:19456
	ds_read_b128 v[202:205], v153 offset:20480
	ds_read_b128 v[206:209], v153 offset:21504
	ds_read_b128 v[210:213], v153 offset:22528
	ds_read_b128 v[214:217], v153 offset:23552
	global_load_lds_dwordx4 v136, s[36:37]
	s_add_i32 m0, s69, 0x2000
	s_add_u32 s70, s36, 0x100000
	s_addc_u32 s71, s37, 0
	s_add_i32 s69, s55, s47
	global_load_lds_dwordx4 v132, s[36:37]
	s_mov_b32 m0, s69
	s_nop 0
	global_load_lds_dwordx4 v136, s[70:71]
	s_add_i32 m0, s69, 0x2000
	s_nop 0
	global_load_lds_dwordx4 v132, s[70:71]
	s_add_u32 s100, s38, s8
	s_addc_u32 s101, s39, s9
	s_mov_b32 m0, s31
	s_nop 0
	global_load_lds_dwordx4 v138, s[38:39]
	s_mov_b32 m0, s48
	s_nop 0
	global_load_lds_dwordx4 v134, s[38:39]
	s_waitcnt vmcnt(8)
	s_waitcnt lgkmcnt(0)
	s_barrier
	s_setprio 1
	s_waitcnt lgkmcnt(0)
	v_mfma_f32_16x16x32_bf16 v[62:65], v[154:157], v[186:189], v[62:65]
	v_mfma_f32_16x16x32_bf16 v[58:61], v[162:165], v[186:189], v[58:61]
	v_mfma_f32_16x16x32_bf16 v[50:53], v[154:157], v[194:197], v[50:53]
	v_mfma_f32_16x16x32_bf16 v[42:45], v[162:165], v[194:197], v[42:45]
	v_mfma_f32_16x16x32_bf16 v[34:37], v[154:157], v[202:205], v[34:37]
	v_mfma_f32_16x16x32_bf16 v[26:29], v[162:165], v[202:205], v[26:29]
	v_mfma_f32_16x16x32_bf16 v[18:21], v[154:157], v[210:213], v[18:21]
	v_mfma_f32_16x16x32_bf16 v[10:13], v[162:165], v[210:213], v[10:13]
	v_mfma_f32_16x16x32_bf16 v[62:65], v[158:161], v[190:193], v[62:65]
	v_mfma_f32_16x16x32_bf16 v[58:61], v[166:169], v[190:193], v[58:61]
	v_mfma_f32_16x16x32_bf16 v[50:53], v[158:161], v[198:201], v[50:53]
	v_mfma_f32_16x16x32_bf16 v[42:45], v[166:169], v[198:201], v[42:45]
	v_mfma_f32_16x16x32_bf16 v[34:37], v[158:161], v[206:209], v[34:37]
	v_mfma_f32_16x16x32_bf16 v[26:29], v[166:169], v[206:209], v[26:29]
	v_mfma_f32_16x16x32_bf16 v[18:21], v[158:161], v[214:217], v[18:21]
	v_mfma_f32_16x16x32_bf16 v[10:13], v[166:169], v[214:217], v[10:13]
	s_setprio 0
	s_setprio 1
	v_mfma_f32_16x16x32_bf16 v[54:57], v[170:173], v[186:189], v[54:57]
	v_mfma_f32_16x16x32_bf16 v[46:49], v[178:181], v[186:189], v[46:49]
	v_mfma_f32_16x16x32_bf16 v[38:41], v[170:173], v[194:197], v[38:41]
	v_mfma_f32_16x16x32_bf16 v[30:33], v[178:181], v[194:197], v[30:33]
	v_mfma_f32_16x16x32_bf16 v[22:25], v[170:173], v[202:205], v[22:25]
	v_mfma_f32_16x16x32_bf16 v[14:17], v[178:181], v[202:205], v[14:17]
	v_mfma_f32_16x16x32_bf16 v[6:9], v[170:173], v[210:213], v[6:9]
	v_mfma_f32_16x16x32_bf16 v[2:5], v[178:181], v[210:213], v[2:5]
	v_mfma_f32_16x16x32_bf16 v[54:57], v[174:177], v[190:193], v[54:57]
	v_mfma_f32_16x16x32_bf16 v[46:49], v[182:185], v[190:193], v[46:49]
	v_mfma_f32_16x16x32_bf16 v[38:41], v[174:177], v[198:201], v[38:41]
	v_mfma_f32_16x16x32_bf16 v[30:33], v[182:185], v[198:201], v[30:33]
	v_mfma_f32_16x16x32_bf16 v[22:25], v[174:177], v[206:209], v[22:25]
	v_mfma_f32_16x16x32_bf16 v[14:17], v[182:185], v[206:209], v[14:17]
	v_mfma_f32_16x16x32_bf16 v[6:9], v[174:177], v[214:217], v[6:9]
	v_mfma_f32_16x16x32_bf16 v[2:5], v[182:185], v[214:217], v[2:5]
	s_setprio 0
	s_barrier
	s_add_i32 s69, 0, 0x18000
	s_add_i32 s70, 0, 0x1c000
	v_add_u32_e32 v166, s69, v131
	v_add_u32_e32 v182, s70, v131
	ds_read_b128 v[154:157], v166
	ds_read_b128 v[158:161], v166 offset:1024
	ds_read_b128 v[162:165], v166 offset:2048
	ds_read_b128 v[166:169], v166 offset:3072
	ds_read_b128 v[170:173], v182
	ds_read_b128 v[174:177], v182 offset:1024
	ds_read_b128 v[178:181], v182 offset:2048
	ds_read_b128 v[182:185], v182 offset:3072
	s_add_u32 s38, s38, 0x100000
	s_addc_u32 s39, s39, 0
	s_mov_b32 m0, s49
	ds_read_b128 v[186:189], v153 offset:32768
	ds_read_b128 v[190:193], v153 offset:33792
	ds_read_b128 v[194:197], v153 offset:34816
	ds_read_b128 v[198:201], v153 offset:35840
	ds_read_b128 v[202:205], v153 offset:36864
	ds_read_b128 v[206:209], v153 offset:37888
	ds_read_b128 v[210:213], v153 offset:38912
	ds_read_b128 v[214:217], v153 offset:39936
	global_load_lds_dwordx4 v138, s[38:39]
	s_mov_b32 m0, s50
	s_nop 0
	global_load_lds_dwordx4 v134, s[38:39]
	s_waitcnt vmcnt(8)
	s_waitcnt lgkmcnt(0)
	s_barrier
	s_setprio 1
	s_waitcnt lgkmcnt(0)
	v_mfma_f32_16x16x32_bf16 v[126:129], v[154:157], v[186:189], v[126:129]
	v_mfma_f32_16x16x32_bf16 v[122:125], v[162:165], v[186:189], v[122:125]
	v_mfma_f32_16x16x32_bf16 v[114:117], v[154:157], v[194:197], v[114:117]
	v_mfma_f32_16x16x32_bf16 v[106:109], v[162:165], v[194:197], v[106:109]
	v_mfma_f32_16x16x32_bf16 v[98:101], v[154:157], v[202:205], v[98:101]
	v_mfma_f32_16x16x32_bf16 v[90:93], v[162:165], v[202:205], v[90:93]
	v_mfma_f32_16x16x32_bf16 v[82:85], v[154:157], v[210:213], v[82:85]
	v_mfma_f32_16x16x32_bf16 v[74:77], v[162:165], v[210:213], v[74:77]
	v_mfma_f32_16x16x32_bf16 v[126:129], v[158:161], v[190:193], v[126:129]
	v_mfma_f32_16x16x32_bf16 v[122:125], v[166:169], v[190:193], v[122:125]
	v_mfma_f32_16x16x32_bf16 v[114:117], v[158:161], v[198:201], v[114:117]
	v_mfma_f32_16x16x32_bf16 v[106:109], v[166:169], v[198:201], v[106:109]
	v_mfma_f32_16x16x32_bf16 v[98:101], v[158:161], v[206:209], v[98:101]
	v_mfma_f32_16x16x32_bf16 v[90:93], v[166:169], v[206:209], v[90:93]
	v_mfma_f32_16x16x32_bf16 v[82:85], v[158:161], v[214:217], v[82:85]
	v_mfma_f32_16x16x32_bf16 v[74:77], v[166:169], v[214:217], v[74:77]
	s_setprio 0
	s_setprio 1
	v_mfma_f32_16x16x32_bf16 v[118:121], v[170:173], v[186:189], v[118:121]
	v_mfma_f32_16x16x32_bf16 v[110:113], v[178:181], v[186:189], v[110:113]
	v_mfma_f32_16x16x32_bf16 v[102:105], v[170:173], v[194:197], v[102:105]
	v_mfma_f32_16x16x32_bf16 v[94:97], v[178:181], v[194:197], v[94:97]
	v_mfma_f32_16x16x32_bf16 v[86:89], v[170:173], v[202:205], v[86:89]
	v_mfma_f32_16x16x32_bf16 v[78:81], v[178:181], v[202:205], v[78:81]
	v_mfma_f32_16x16x32_bf16 v[70:73], v[170:173], v[210:213], v[70:73]
	v_mfma_f32_16x16x32_bf16 v[66:69], v[178:181], v[210:213], v[66:69]
	v_mfma_f32_16x16x32_bf16 v[118:121], v[174:177], v[190:193], v[118:121]
	v_mfma_f32_16x16x32_bf16 v[110:113], v[182:185], v[190:193], v[110:113]
	v_mfma_f32_16x16x32_bf16 v[102:105], v[174:177], v[198:201], v[102:105]
	v_mfma_f32_16x16x32_bf16 v[94:97], v[182:185], v[198:201], v[94:97]
	v_mfma_f32_16x16x32_bf16 v[86:89], v[174:177], v[206:209], v[86:89]
	v_mfma_f32_16x16x32_bf16 v[78:81], v[182:185], v[206:209], v[78:81]
	v_mfma_f32_16x16x32_bf16 v[70:73], v[174:177], v[214:217], v[70:73]
	v_mfma_f32_16x16x32_bf16 v[66:69], v[182:185], v[214:217], v[66:69]
	s_setprio 0
	s_barrier
	s_add_i32 s38, s69, s47
	s_mov_b32 m0, s38
	ds_read_b128 v[186:189], v153 offset:49152
	ds_read_b128 v[190:193], v153 offset:50176
	ds_read_b128 v[194:197], v153 offset:51200
	ds_read_b128 v[198:201], v153 offset:52224
	ds_read_b128 v[202:205], v153 offset:53248
	ds_read_b128 v[206:209], v153 offset:54272
	ds_read_b128 v[210:213], v153 offset:55296
	ds_read_b128 v[214:217], v153 offset:56320
	global_load_lds_dwordx4 v136, s[98:99]
	s_add_i32 m0, s38, 0x2000
	s_add_u32 s36, s36, 0x100080
	s_addc_u32 s37, s37, 0
	s_add_i32 s38, s70, s47
	global_load_lds_dwordx4 v132, s[98:99]
	s_mov_b32 m0, s38
	s_nop 0
	global_load_lds_dwordx4 v136, s[36:37]
	s_add_i32 m0, s38, 0x2000
	s_nop 0
	global_load_lds_dwordx4 v132, s[36:37]
	s_mov_b32 m0, s52
	s_nop 0
	global_load_lds_dwordx4 v138, s[100:101]
	s_mov_b32 m0, s53
	s_nop 0
	global_load_lds_dwordx4 v134, s[100:101]
	s_waitcnt vmcnt(8)
	s_waitcnt lgkmcnt(0)
	s_barrier
	s_setprio 1
	s_waitcnt lgkmcnt(0)
	v_mfma_f32_16x16x32_bf16 v[62:65], v[154:157], v[186:189], v[62:65]
	v_mfma_f32_16x16x32_bf16 v[58:61], v[162:165], v[186:189], v[58:61]
	v_mfma_f32_16x16x32_bf16 v[50:53], v[154:157], v[194:197], v[50:53]
	v_mfma_f32_16x16x32_bf16 v[42:45], v[162:165], v[194:197], v[42:45]
	v_mfma_f32_16x16x32_bf16 v[34:37], v[154:157], v[202:205], v[34:37]
	v_mfma_f32_16x16x32_bf16 v[26:29], v[162:165], v[202:205], v[26:29]
	v_mfma_f32_16x16x32_bf16 v[18:21], v[154:157], v[210:213], v[18:21]
	v_mfma_f32_16x16x32_bf16 v[10:13], v[162:165], v[210:213], v[10:13]
	v_mfma_f32_16x16x32_bf16 v[62:65], v[158:161], v[190:193], v[62:65]
	v_mfma_f32_16x16x32_bf16 v[58:61], v[166:169], v[190:193], v[58:61]
	v_mfma_f32_16x16x32_bf16 v[50:53], v[158:161], v[198:201], v[50:53]
	v_mfma_f32_16x16x32_bf16 v[42:45], v[166:169], v[198:201], v[42:45]
	v_mfma_f32_16x16x32_bf16 v[34:37], v[158:161], v[206:209], v[34:37]
	v_mfma_f32_16x16x32_bf16 v[26:29], v[166:169], v[206:209], v[26:29]
	v_mfma_f32_16x16x32_bf16 v[18:21], v[158:161], v[214:217], v[18:21]
	v_mfma_f32_16x16x32_bf16 v[10:13], v[166:169], v[214:217], v[10:13]
	s_setprio 0
	s_setprio 1
	v_mfma_f32_16x16x32_bf16 v[54:57], v[170:173], v[186:189], v[54:57]
	v_mfma_f32_16x16x32_bf16 v[46:49], v[178:181], v[186:189], v[46:49]
	v_mfma_f32_16x16x32_bf16 v[38:41], v[170:173], v[194:197], v[38:41]
	v_mfma_f32_16x16x32_bf16 v[30:33], v[178:181], v[194:197], v[30:33]
	v_mfma_f32_16x16x32_bf16 v[22:25], v[170:173], v[202:205], v[22:25]
	v_mfma_f32_16x16x32_bf16 v[14:17], v[178:181], v[202:205], v[14:17]
	v_mfma_f32_16x16x32_bf16 v[6:9], v[170:173], v[210:213], v[6:9]
	v_mfma_f32_16x16x32_bf16 v[2:5], v[178:181], v[210:213], v[2:5]
	v_mfma_f32_16x16x32_bf16 v[54:57], v[174:177], v[190:193], v[54:57]
	v_mfma_f32_16x16x32_bf16 v[46:49], v[182:185], v[190:193], v[46:49]
	v_mfma_f32_16x16x32_bf16 v[38:41], v[174:177], v[198:201], v[38:41]
	v_mfma_f32_16x16x32_bf16 v[30:33], v[182:185], v[198:201], v[30:33]
	v_mfma_f32_16x16x32_bf16 v[22:25], v[174:177], v[206:209], v[22:25]
	v_mfma_f32_16x16x32_bf16 v[14:17], v[182:185], v[206:209], v[14:17]
	v_mfma_f32_16x16x32_bf16 v[6:9], v[174:177], v[214:217], v[6:9]
	v_mfma_f32_16x16x32_bf16 v[2:5], v[182:185], v[214:217], v[2:5]
	s_setprio 0
	s_barrier
	s_add_i32 s68, s68, 2
	s_add_u32 s34, s34, 0x100
	s_addc_u32 s35, s35, 0
	s_add_u32 s63, s63, 0x100
	s_addc_u32 s65, s65, 0
	s_cmp_gt_u32 s68, 61
	s_cbranch_scc0 .LBB0_668
	s_and_b64 vcc, exec, s[12:13]
	s_cbranch_vccz .LBB0_671
	s_barrier

.LBB0_845:
	ds_read_b128 v[130:133], v238
	ds_read_b128 v[134:137], v238 offset:1024
	ds_read_b128 v[138:141], v238 offset:2048
	ds_read_b128 v[142:145], v238 offset:3072
	ds_read_b128 v[146:149], v239
	ds_read_b128 v[150:153], v239 offset:1024
	ds_read_b128 v[154:157], v239 offset:2048
	ds_read_b128 v[158:161], v239 offset:3072
	s_add_u32 s56, s2, 0x100
	s_addc_u32 s57, s3, 0
	s_cmp_eq_u32 s92, 28
	s_cselect_b32 s61, s49, s57
	s_cselect_b32 s60, s88, s56
	s_cselect_b32 s59, s47, s91
	s_cselect_b32 s58, s89, s90
	s_add_i32 m0, s55, 0xc000
	ds_read_b128 v[162:165], v240
	ds_read_b128 v[166:169], v240 offset:1024
	ds_read_b128 v[170:173], v240 offset:2048
	ds_read_b128 v[174:177], v240 offset:3072
	ds_read_b128 v[178:181], v240 offset:4096
	ds_read_b128 v[182:185], v240 offset:5120
	ds_read_b128 v[186:189], v240 offset:6144
	ds_read_b128 v[190:193], v240 offset:7168
	global_load_lds_dwordx4 v210, s[2:3]
	s_add_i32 m0, s55, 0xe000
	s_nop 0
	global_load_lds_dwordx4 v212, s[2:3]
	s_waitcnt vmcnt(8)
	s_waitcnt lgkmcnt(0)
	s_barrier
	s_setprio 1
	s_waitcnt lgkmcnt(0)
	v_mfma_i32_16x16x64_i8 v[126:129], v[130:133], v[162:165], v[126:129]
	v_mfma_i32_16x16x64_i8 v[122:125], v[138:141], v[162:165], v[122:125]
	v_mfma_i32_16x16x64_i8 v[118:121], v[130:133], v[170:173], v[118:121]
	v_mfma_i32_16x16x64_i8 v[110:113], v[138:141], v[170:173], v[110:113]
	v_mfma_i32_16x16x64_i8 v[78:81], v[130:133], v[178:181], v[78:81]
	v_mfma_i32_16x16x64_i8 v[30:33], v[138:141], v[178:181], v[30:33]
	v_mfma_i32_16x16x64_i8 v[74:77], v[130:133], v[186:189], v[74:77]
	v_mfma_i32_16x16x64_i8 v[26:29], v[138:141], v[186:189], v[26:29]
	v_mfma_i32_16x16x64_i8 v[126:129], v[134:137], v[166:169], v[126:129]
	v_mfma_i32_16x16x64_i8 v[122:125], v[142:145], v[166:169], v[122:125]
	v_mfma_i32_16x16x64_i8 v[118:121], v[134:137], v[174:177], v[118:121]
	v_mfma_i32_16x16x64_i8 v[110:113], v[142:145], v[174:177], v[110:113]
	v_mfma_i32_16x16x64_i8 v[78:81], v[134:137], v[182:185], v[78:81]
	v_mfma_i32_16x16x64_i8 v[30:33], v[142:145], v[182:185], v[30:33]
	v_mfma_i32_16x16x64_i8 v[74:77], v[134:137], v[190:193], v[74:77]
	v_mfma_i32_16x16x64_i8 v[26:29], v[142:145], v[190:193], v[26:29]
	s_setprio 0
	s_setprio 1
	v_mfma_i32_16x16x64_i8 v[102:105], v[146:149], v[162:165], v[102:105]
	v_mfma_i32_16x16x64_i8 v[98:101], v[154:157], v[162:165], v[98:101]
	v_mfma_i32_16x16x64_i8 v[94:97], v[146:149], v[170:173], v[94:97]
	v_mfma_i32_16x16x64_i8 v[90:93], v[154:157], v[170:173], v[90:93]
	v_mfma_i32_16x16x64_i8 v[70:73], v[146:149], v[178:181], v[70:73]
	v_mfma_i32_16x16x64_i8 v[22:25], v[154:157], v[178:181], v[22:25]
	v_mfma_i32_16x16x64_i8 v[66:69], v[146:149], v[186:189], v[66:69]
	v_mfma_i32_16x16x64_i8 v[18:21], v[154:157], v[186:189], v[18:21]
	v_mfma_i32_16x16x64_i8 v[102:105], v[150:153], v[166:169], v[102:105]
	v_mfma_i32_16x16x64_i8 v[98:101], v[158:161], v[166:169], v[98:101]
	v_mfma_i32_16x16x64_i8 v[94:97], v[150:153], v[174:177], v[94:97]
	v_mfma_i32_16x16x64_i8 v[90:93], v[158:161], v[174:177], v[90:93]
	v_mfma_i32_16x16x64_i8 v[70:73], v[150:153], v[182:185], v[70:73]
	v_mfma_i32_16x16x64_i8 v[22:25], v[158:161], v[182:185], v[22:25]
	v_mfma_i32_16x16x64_i8 v[66:69], v[150:153], v[190:193], v[66:69]
	v_mfma_i32_16x16x64_i8 v[18:21], v[158:161], v[190:193], v[18:21]
	s_setprio 0
	s_barrier
	s_add_i32 s2, s84, s65
	s_add_u32 s98, s58, s36
	s_addc_u32 s99, s59, s37
	s_mov_b32 m0, s2
	ds_read_b128 v[162:165], v240 offset:16384
	ds_read_b128 v[166:169], v240 offset:17408
	ds_read_b128 v[170:173], v240 offset:18432
	ds_read_b128 v[174:177], v240 offset:19456
	ds_read_b128 v[178:181], v240 offset:20480
	ds_read_b128 v[182:185], v240 offset:21504
	ds_read_b128 v[186:189], v240 offset:22528
	ds_read_b128 v[190:193], v240 offset:23552
	global_load_lds_dwordx4 v206, s[58:59]
	s_add_i32 m0, s2, 0x2000
	s_add_u32 s2, s58, 0x80000
	s_addc_u32 s3, s59, 0
	s_add_i32 s93, s85, s65
	global_load_lds_dwordx4 v202, s[58:59]
	s_mov_b32 m0, s93
	s_nop 0
	global_load_lds_dwordx4 v206, s[2:3]
	s_add_i32 m0, s93, 0x2000
	s_nop 0
	global_load_lds_dwordx4 v202, s[2:3]
	s_add_u32 s100, s60, s36
	s_addc_u32 s101, s61, s37
	s_mov_b32 m0, s55
	s_nop 0
	global_load_lds_dwordx4 v208, s[60:61]
	s_mov_b32 m0, s69
	s_nop 0
	global_load_lds_dwordx4 v204, s[60:61]
	s_waitcnt vmcnt(8)
	s_waitcnt lgkmcnt(0)
	s_barrier
	s_setprio 1
	s_waitcnt lgkmcnt(0)
	v_mfma_i32_16x16x64_i8 v[62:65], v[130:133], v[162:165], v[62:65]
	v_mfma_i32_16x16x64_i8 v[14:17], v[138:141], v[162:165], v[14:17]
	v_mfma_i32_16x16x64_i8 v[58:61], v[130:133], v[170:173], v[58:61]
	v_mfma_i32_16x16x64_i8 v[10:13], v[138:141], v[170:173], v[10:13]
	v_mfma_i32_16x16x64_i8 v[114:117], v[130:133], v[178:181], v[114:117]
	v_mfma_i32_16x16x64_i8 v[106:109], v[138:141], v[178:181], v[106:109]
	v_mfma_i32_16x16x64_i8 v[86:89], v[130:133], v[186:189], v[86:89]
	v_mfma_i32_16x16x64_i8 v[82:85], v[138:141], v[186:189], v[82:85]
	v_mfma_i32_16x16x64_i8 v[62:65], v[134:137], v[166:169], v[62:65]
	v_mfma_i32_16x16x64_i8 v[14:17], v[142:145], v[166:169], v[14:17]
	v_mfma_i32_16x16x64_i8 v[58:61], v[134:137], v[174:177], v[58:61]
	v_mfma_i32_16x16x64_i8 v[10:13], v[142:145], v[174:177], v[10:13]
	v_mfma_i32_16x16x64_i8 v[114:117], v[134:137], v[182:185], v[114:117]
	v_mfma_i32_16x16x64_i8 v[106:109], v[142:145], v[182:185], v[106:109]
	v_mfma_i32_16x16x64_i8 v[86:89], v[134:137], v[190:193], v[86:89]
	v_mfma_i32_16x16x64_i8 v[82:85], v[142:145], v[190:193], v[82:85]
	s_setprio 0
	s_setprio 1
	v_mfma_i32_16x16x64_i8 v[50:53], v[146:149], v[162:165], v[50:53]
	v_mfma_i32_16x16x64_i8 v[6:9], v[154:157], v[162:165], v[6:9]
	v_mfma_i32_16x16x64_i8 v[42:45], v[146:149], v[170:173], v[42:45]
	v_mfma_i32_16x16x64_i8 v[2:5], v[154:157], v[170:173], v[2:5]
	v_mfma_i32_16x16x64_i8 v[54:57], v[146:149], v[178:181], v[54:57]
	v_mfma_i32_16x16x64_i8 v[46:49], v[154:157], v[178:181], v[46:49]
	v_mfma_i32_16x16x64_i8 v[38:41], v[146:149], v[186:189], v[38:41]
	v_mfma_i32_16x16x64_i8 v[34:37], v[154:157], v[186:189], v[34:37]
	v_mfma_i32_16x16x64_i8 v[50:53], v[150:153], v[166:169], v[50:53]
	v_mfma_i32_16x16x64_i8 v[6:9], v[158:161], v[166:169], v[6:9]
	v_mfma_i32_16x16x64_i8 v[42:45], v[150:153], v[174:177], v[42:45]
	v_mfma_i32_16x16x64_i8 v[2:5], v[158:161], v[174:177], v[2:5]
	v_mfma_i32_16x16x64_i8 v[54:57], v[150:153], v[182:185], v[54:57]
	v_mfma_i32_16x16x64_i8 v[46:49], v[158:161], v[182:185], v[46:49]
	v_mfma_i32_16x16x64_i8 v[38:41], v[150:153], v[190:193], v[38:41]
	v_mfma_i32_16x16x64_i8 v[34:37], v[158:161], v[190:193], v[34:37]
	s_setprio 0
	s_barrier
	s_add_i32 s93, 0, 0x18000
	s_add_i32 s94, 0, 0x1c000
	v_add_u32_e32 v142, s93, v237
	v_add_u32_e32 v158, s94, v237
	ds_read_b128 v[130:133], v142
	ds_read_b128 v[134:137], v142 offset:1024
	ds_read_b128 v[138:141], v142 offset:2048
	ds_read_b128 v[142:145], v142 offset:3072
	ds_read_b128 v[146:149], v158
	ds_read_b128 v[150:153], v158 offset:1024
	ds_read_b128 v[154:157], v158 offset:2048
	ds_read_b128 v[158:161], v158 offset:3072
	s_add_u32 s2, s60, 0x4000
	s_addc_u32 s3, s61, 0
	s_mov_b32 m0, s70
	ds_read_b128 v[162:165], v240 offset:32768
	ds_read_b128 v[166:169], v240 offset:33792
	ds_read_b128 v[170:173], v240 offset:34816
	ds_read_b128 v[174:177], v240 offset:35840
	ds_read_b128 v[178:181], v240 offset:36864
	ds_read_b128 v[182:185], v240 offset:37888
	ds_read_b128 v[186:189], v240 offset:38912
	ds_read_b128 v[190:193], v240 offset:39936
	global_load_lds_dwordx4 v208, s[2:3]
	s_mov_b32 m0, s71
	s_nop 0
	global_load_lds_dwordx4 v204, s[2:3]
	s_waitcnt vmcnt(8)
	s_waitcnt lgkmcnt(0)
	s_barrier
	s_setprio 1
	s_waitcnt lgkmcnt(0)
	v_mfma_i32_16x16x64_i8 v[126:129], v[130:133], v[162:165], v[126:129]
	v_mfma_i32_16x16x64_i8 v[122:125], v[138:141], v[162:165], v[122:125]
	v_mfma_i32_16x16x64_i8 v[118:121], v[130:133], v[170:173], v[118:121]
	v_mfma_i32_16x16x64_i8 v[110:113], v[138:141], v[170:173], v[110:113]
	v_mfma_i32_16x16x64_i8 v[78:81], v[130:133], v[178:181], v[78:81]
	v_mfma_i32_16x16x64_i8 v[30:33], v[138:141], v[178:181], v[30:33]
	v_mfma_i32_16x16x64_i8 v[74:77], v[130:133], v[186:189], v[74:77]
	v_mfma_i32_16x16x64_i8 v[26:29], v[138:141], v[186:189], v[26:29]
	v_mfma_i32_16x16x64_i8 v[126:129], v[134:137], v[166:169], v[126:129]
	v_mfma_i32_16x16x64_i8 v[122:125], v[142:145], v[166:169], v[122:125]
	v_mfma_i32_16x16x64_i8 v[118:121], v[134:137], v[174:177], v[118:121]
	v_mfma_i32_16x16x64_i8 v[110:113], v[142:145], v[174:177], v[110:113]
	v_mfma_i32_16x16x64_i8 v[78:81], v[134:137], v[182:185], v[78:81]
	v_mfma_i32_16x16x64_i8 v[30:33], v[142:145], v[182:185], v[30:33]
	v_mfma_i32_16x16x64_i8 v[74:77], v[134:137], v[190:193], v[74:77]
	v_mfma_i32_16x16x64_i8 v[26:29], v[142:145], v[190:193], v[26:29]
	s_setprio 0
	s_setprio 1
	v_mfma_i32_16x16x64_i8 v[102:105], v[146:149], v[162:165], v[102:105]
	v_mfma_i32_16x16x64_i8 v[98:101], v[154:157], v[162:165], v[98:101]
	v_mfma_i32_16x16x64_i8 v[94:97], v[146:149], v[170:173], v[94:97]
	v_mfma_i32_16x16x64_i8 v[90:93], v[154:157], v[170:173], v[90:93]
	v_mfma_i32_16x16x64_i8 v[70:73], v[146:149], v[178:181], v[70:73]
	v_mfma_i32_16x16x64_i8 v[22:25], v[154:157], v[178:181], v[22:25]
	v_mfma_i32_16x16x64_i8 v[66:69], v[146:149], v[186:189], v[66:69]
	v_mfma_i32_16x16x64_i8 v[18:21], v[154:157], v[186:189], v[18:21]
	v_mfma_i32_16x16x64_i8 v[102:105], v[150:153], v[166:169], v[102:105]
	v_mfma_i32_16x16x64_i8 v[98:101], v[158:161], v[166:169], v[98:101]
	v_mfma_i32_16x16x64_i8 v[94:97], v[150:153], v[174:177], v[94:97]
	v_mfma_i32_16x16x64_i8 v[90:93], v[158:161], v[174:177], v[90:93]
	v_mfma_i32_16x16x64_i8 v[70:73], v[150:153], v[182:185], v[70:73]
	v_mfma_i32_16x16x64_i8 v[22:25], v[158:161], v[182:185], v[22:25]
	v_mfma_i32_16x16x64_i8 v[66:69], v[150:153], v[190:193], v[66:69]
	v_mfma_i32_16x16x64_i8 v[18:21], v[158:161], v[190:193], v[18:21]
	s_setprio 0
	s_barrier
	s_add_i32 s2, s93, s65
	s_mov_b32 m0, s2
	ds_read_b128 v[162:165], v240 offset:49152
	ds_read_b128 v[166:169], v240 offset:50176
	ds_read_b128 v[170:173], v240 offset:51200
	ds_read_b128 v[174:177], v240 offset:52224
	ds_read_b128 v[178:181], v240 offset:53248
	ds_read_b128 v[182:185], v240 offset:54272
	ds_read_b128 v[186:189], v240 offset:55296
	ds_read_b128 v[190:193], v240 offset:56320
	global_load_lds_dwordx4 v206, s[98:99]
	s_add_i32 m0, s2, 0x2000
	s_add_u32 s2, s58, 0x80080
	s_addc_u32 s3, s59, 0
	s_add_i32 s58, s94, s65
	global_load_lds_dwordx4 v202, s[98:99]
	s_mov_b32 m0, s58
	s_nop 0
	global_load_lds_dwordx4 v206, s[2:3]
	s_add_i32 m0, s58, 0x2000
	s_nop 0
	global_load_lds_dwordx4 v202, s[2:3]
	s_mov_b32 m0, s78
	s_nop 0
	global_load_lds_dwordx4 v208, s[100:101]
	s_mov_b32 m0, s79
	s_nop 0
	global_load_lds_dwordx4 v204, s[100:101]
	s_waitcnt vmcnt(8)
	s_waitcnt lgkmcnt(0)
	s_barrier
	s_setprio 1
	s_waitcnt lgkmcnt(0)
	v_mfma_i32_16x16x64_i8 v[62:65], v[130:133], v[162:165], v[62:65]
	v_mfma_i32_16x16x64_i8 v[14:17], v[138:141], v[162:165], v[14:17]
	v_mfma_i32_16x16x64_i8 v[58:61], v[130:133], v[170:173], v[58:61]
	v_mfma_i32_16x16x64_i8 v[10:13], v[138:141], v[170:173], v[10:13]
	v_mfma_i32_16x16x64_i8 v[114:117], v[130:133], v[178:181], v[114:117]
	v_mfma_i32_16x16x64_i8 v[106:109], v[138:141], v[178:181], v[106:109]
	v_mfma_i32_16x16x64_i8 v[86:89], v[130:133], v[186:189], v[86:89]
	v_mfma_i32_16x16x64_i8 v[82:85], v[138:141], v[186:189], v[82:85]
	v_mfma_i32_16x16x64_i8 v[62:65], v[134:137], v[166:169], v[62:65]
	v_mfma_i32_16x16x64_i8 v[14:17], v[142:145], v[166:169], v[14:17]
	v_mfma_i32_16x16x64_i8 v[58:61], v[134:137], v[174:177], v[58:61]
	v_mfma_i32_16x16x64_i8 v[10:13], v[142:145], v[174:177], v[10:13]
	v_mfma_i32_16x16x64_i8 v[114:117], v[134:137], v[182:185], v[114:117]
	v_mfma_i32_16x16x64_i8 v[106:109], v[142:145], v[182:185], v[106:109]
	v_mfma_i32_16x16x64_i8 v[86:89], v[134:137], v[190:193], v[86:89]
	v_mfma_i32_16x16x64_i8 v[82:85], v[142:145], v[190:193], v[82:85]
	s_setprio 0
	s_setprio 1
	v_mfma_i32_16x16x64_i8 v[50:53], v[146:149], v[162:165], v[50:53]
	v_mfma_i32_16x16x64_i8 v[6:9], v[154:157], v[162:165], v[6:9]
	v_mfma_i32_16x16x64_i8 v[42:45], v[146:149], v[170:173], v[42:45]
	v_mfma_i32_16x16x64_i8 v[2:5], v[154:157], v[170:173], v[2:5]
	v_mfma_i32_16x16x64_i8 v[54:57], v[146:149], v[178:181], v[54:57]
	v_mfma_i32_16x16x64_i8 v[46:49], v[154:157], v[178:181], v[46:49]
	v_mfma_i32_16x16x64_i8 v[38:41], v[146:149], v[186:189], v[38:41]
	v_mfma_i32_16x16x64_i8 v[34:37], v[154:157], v[186:189], v[34:37]
	v_mfma_i32_16x16x64_i8 v[50:53], v[150:153], v[166:169], v[50:53]
	v_mfma_i32_16x16x64_i8 v[6:9], v[158:161], v[166:169], v[6:9]
	v_mfma_i32_16x16x64_i8 v[42:45], v[150:153], v[174:177], v[42:45]
	v_mfma_i32_16x16x64_i8 v[2:5], v[158:161], v[174:177], v[2:5]
	v_mfma_i32_16x16x64_i8 v[54:57], v[150:153], v[182:185], v[54:57]
	v_mfma_i32_16x16x64_i8 v[46:49], v[158:161], v[182:185], v[46:49]
	v_mfma_i32_16x16x64_i8 v[38:41], v[150:153], v[190:193], v[38:41]
	v_mfma_i32_16x16x64_i8 v[34:37], v[158:161], v[190:193], v[34:37]
	s_setprio 0
	s_barrier
	s_add_i32 s92, s92, 2
	s_add_u32 s90, s90, 0x100
	s_addc_u32 s91, s91, 0
	s_cmp_gt_u32 s92, 29
	s_mov_b64 s[2:3], s[56:57]
	s_cbranch_scc0 .LBB0_845
	s_and_b64 vcc, exec, s[38:39]
	s_cbranch_vccz .LBB0_848
	s_barrier

.LBB0_1099:
	ds_read_b128 v[130:133], v167
	ds_read_b128 v[134:137], v167 offset:1024
	ds_read_b128 v[138:141], v167 offset:2048
	ds_read_b128 v[142:145], v167 offset:3072
	ds_read_b128 v[170:173], v168
	ds_read_b128 v[174:177], v168 offset:1024
	ds_read_b128 v[178:181], v168 offset:2048
	ds_read_b128 v[182:185], v168 offset:3072
	s_add_u32 s30, s28, 0x100
	s_addc_u32 s31, s29, 0
	s_cmpk_eq_i32 s72, 0x52
	s_cselect_b32 s37, s3, s31
	s_cselect_b32 s36, s2, s30
	s_cselect_b32 s35, s27, s71
	s_cselect_b32 s34, s26, s70
	s_add_i32 m0, s47, 0xc000
	ds_read_b128 v[186:189], v169
	ds_read_b128 v[190:193], v169 offset:1024
	ds_read_b128 v[194:197], v169 offset:2048
	ds_read_b128 v[198:201], v169 offset:3072
	ds_read_b128 v[202:205], v169 offset:4096
	ds_read_b128 v[206:209], v169 offset:5120
	ds_read_b128 v[210:213], v169 offset:6144
	ds_read_b128 v[214:217], v169 offset:7168
	global_load_lds_dwordx4 v154, s[28:29]
	s_add_i32 m0, s47, 0xe000
	s_nop 0
	global_load_lds_dwordx4 v156, s[28:29]
	s_waitcnt vmcnt(8)
	s_waitcnt lgkmcnt(0)
	s_barrier
	s_setprio 1
	s_waitcnt lgkmcnt(0)
	v_mfma_i32_16x16x64_i8 v[126:129], v[130:133], v[186:189], v[126:129]
	v_mfma_i32_16x16x64_i8 v[122:125], v[138:141], v[186:189], v[122:125]
	v_mfma_i32_16x16x64_i8 v[110:113], v[130:133], v[194:197], v[110:113]
	v_mfma_i32_16x16x64_i8 v[106:109], v[138:141], v[194:197], v[106:109]
	v_mfma_i32_16x16x64_i8 v[94:97], v[130:133], v[202:205], v[94:97]
	v_mfma_i32_16x16x64_i8 v[90:93], v[138:141], v[202:205], v[90:93]
	v_mfma_i32_16x16x64_i8 v[78:81], v[130:133], v[210:213], v[78:81]
	v_mfma_i32_16x16x64_i8 v[74:77], v[138:141], v[210:213], v[74:77]
	v_mfma_i32_16x16x64_i8 v[126:129], v[134:137], v[190:193], v[126:129]
	v_mfma_i32_16x16x64_i8 v[122:125], v[142:145], v[190:193], v[122:125]
	v_mfma_i32_16x16x64_i8 v[110:113], v[134:137], v[198:201], v[110:113]
	v_mfma_i32_16x16x64_i8 v[106:109], v[142:145], v[198:201], v[106:109]
	v_mfma_i32_16x16x64_i8 v[94:97], v[134:137], v[206:209], v[94:97]
	v_mfma_i32_16x16x64_i8 v[90:93], v[142:145], v[206:209], v[90:93]
	v_mfma_i32_16x16x64_i8 v[78:81], v[134:137], v[214:217], v[78:81]
	v_mfma_i32_16x16x64_i8 v[74:77], v[142:145], v[214:217], v[74:77]
	s_setprio 0
	s_setprio 1
	v_mfma_i32_16x16x64_i8 v[118:121], v[170:173], v[186:189], v[118:121]
	v_mfma_i32_16x16x64_i8 v[114:117], v[178:181], v[186:189], v[114:117]
	v_mfma_i32_16x16x64_i8 v[102:105], v[170:173], v[194:197], v[102:105]
	v_mfma_i32_16x16x64_i8 v[98:101], v[178:181], v[194:197], v[98:101]
	v_mfma_i32_16x16x64_i8 v[86:89], v[170:173], v[202:205], v[86:89]
	v_mfma_i32_16x16x64_i8 v[82:85], v[178:181], v[202:205], v[82:85]
	v_mfma_i32_16x16x64_i8 v[70:73], v[170:173], v[210:213], v[70:73]
	v_mfma_i32_16x16x64_i8 v[66:69], v[178:181], v[210:213], v[66:69]
	v_mfma_i32_16x16x64_i8 v[118:121], v[174:177], v[190:193], v[118:121]
	v_mfma_i32_16x16x64_i8 v[114:117], v[182:185], v[190:193], v[114:117]
	v_mfma_i32_16x16x64_i8 v[102:105], v[174:177], v[198:201], v[102:105]
	v_mfma_i32_16x16x64_i8 v[98:101], v[182:185], v[198:201], v[98:101]
	v_mfma_i32_16x16x64_i8 v[86:89], v[174:177], v[206:209], v[86:89]
	v_mfma_i32_16x16x64_i8 v[82:85], v[182:185], v[206:209], v[82:85]
	v_mfma_i32_16x16x64_i8 v[70:73], v[174:177], v[214:217], v[70:73]
	v_mfma_i32_16x16x64_i8 v[66:69], v[182:185], v[214:217], v[66:69]
	s_setprio 0
	s_barrier
	s_add_i32 s28, s56, s46
	s_add_u32 s98, s34, s14
	s_addc_u32 s99, s35, s15
	s_mov_b32 m0, s28
	ds_read_b128 v[186:189], v169 offset:16384
	ds_read_b128 v[190:193], v169 offset:17408
	ds_read_b128 v[194:197], v169 offset:18432
	ds_read_b128 v[198:201], v169 offset:19456
	ds_read_b128 v[202:205], v169 offset:20480
	ds_read_b128 v[206:209], v169 offset:21504
	ds_read_b128 v[210:213], v169 offset:22528
	ds_read_b128 v[214:217], v169 offset:23552
	global_load_lds_dwordx4 v150, s[34:35]
	s_add_i32 m0, s28, 0x2000
	s_add_u32 s28, s34, 0x158000
	s_addc_u32 s29, s35, 0
	s_add_i32 s73, s57, s46
	global_load_lds_dwordx4 v146, s[34:35]
	s_mov_b32 m0, s73
	s_nop 0
	global_load_lds_dwordx4 v150, s[28:29]
	s_add_i32 m0, s73, 0x2000
	s_nop 0
	global_load_lds_dwordx4 v146, s[28:29]
	s_add_u32 s100, s36, s14
	s_addc_u32 s101, s37, s15
	s_mov_b32 m0, s47
	s_nop 0
	global_load_lds_dwordx4 v152, s[36:37]
	s_mov_b32 m0, s48
	s_nop 0
	global_load_lds_dwordx4 v148, s[36:37]
	s_waitcnt vmcnt(8)
	s_waitcnt lgkmcnt(0)
	s_barrier
	s_setprio 1
	s_waitcnt lgkmcnt(0)
	v_mfma_i32_16x16x64_i8 v[62:65], v[130:133], v[186:189], v[62:65]
	v_mfma_i32_16x16x64_i8 v[58:61], v[138:141], v[186:189], v[58:61]
	v_mfma_i32_16x16x64_i8 v[46:49], v[130:133], v[194:197], v[46:49]
	v_mfma_i32_16x16x64_i8 v[42:45], v[138:141], v[194:197], v[42:45]
	v_mfma_i32_16x16x64_i8 v[30:33], v[130:133], v[202:205], v[30:33]
	v_mfma_i32_16x16x64_i8 v[26:29], v[138:141], v[202:205], v[26:29]
	v_mfma_i32_16x16x64_i8 v[14:17], v[130:133], v[210:213], v[14:17]
	v_mfma_i32_16x16x64_i8 v[10:13], v[138:141], v[210:213], v[10:13]
	v_mfma_i32_16x16x64_i8 v[62:65], v[134:137], v[190:193], v[62:65]
	v_mfma_i32_16x16x64_i8 v[58:61], v[142:145], v[190:193], v[58:61]
	v_mfma_i32_16x16x64_i8 v[46:49], v[134:137], v[198:201], v[46:49]
	v_mfma_i32_16x16x64_i8 v[42:45], v[142:145], v[198:201], v[42:45]
	v_mfma_i32_16x16x64_i8 v[30:33], v[134:137], v[206:209], v[30:33]
	v_mfma_i32_16x16x64_i8 v[26:29], v[142:145], v[206:209], v[26:29]
	v_mfma_i32_16x16x64_i8 v[14:17], v[134:137], v[214:217], v[14:17]
	v_mfma_i32_16x16x64_i8 v[10:13], v[142:145], v[214:217], v[10:13]
	s_setprio 0
	s_setprio 1
	v_mfma_i32_16x16x64_i8 v[54:57], v[170:173], v[186:189], v[54:57]
	v_mfma_i32_16x16x64_i8 v[50:53], v[178:181], v[186:189], v[50:53]
	v_mfma_i32_16x16x64_i8 v[38:41], v[170:173], v[194:197], v[38:41]
	v_mfma_i32_16x16x64_i8 v[34:37], v[178:181], v[194:197], v[34:37]
	v_mfma_i32_16x16x64_i8 v[22:25], v[170:173], v[202:205], v[22:25]
	v_mfma_i32_16x16x64_i8 v[18:21], v[178:181], v[202:205], v[18:21]
	v_mfma_i32_16x16x64_i8 v[6:9], v[170:173], v[210:213], v[6:9]
	v_mfma_i32_16x16x64_i8 v[2:5], v[178:181], v[210:213], v[2:5]
	v_mfma_i32_16x16x64_i8 v[54:57], v[174:177], v[190:193], v[54:57]
	v_mfma_i32_16x16x64_i8 v[50:53], v[182:185], v[190:193], v[50:53]
	v_mfma_i32_16x16x64_i8 v[38:41], v[174:177], v[198:201], v[38:41]
	v_mfma_i32_16x16x64_i8 v[34:37], v[182:185], v[198:201], v[34:37]
	v_mfma_i32_16x16x64_i8 v[22:25], v[174:177], v[206:209], v[22:25]
	v_mfma_i32_16x16x64_i8 v[18:21], v[182:185], v[206:209], v[18:21]
	v_mfma_i32_16x16x64_i8 v[6:9], v[174:177], v[214:217], v[6:9]
	v_mfma_i32_16x16x64_i8 v[2:5], v[182:185], v[214:217], v[2:5]
	s_setprio 0
	s_barrier
	s_add_i32 s73, 0, 0x18000
	s_add_i32 s74, 0, 0x1c000
	v_add_u32_e32 v142, s73, v166
	v_add_u32_e32 v182, s74, v166
	ds_read_b128 v[130:133], v142
	ds_read_b128 v[134:137], v142 offset:1024
	ds_read_b128 v[138:141], v142 offset:2048
	ds_read_b128 v[142:145], v142 offset:3072
	ds_read_b128 v[170:173], v182
	ds_read_b128 v[174:177], v182 offset:1024
	ds_read_b128 v[178:181], v182 offset:2048
	ds_read_b128 v[182:185], v182 offset:3072
	s_add_u32 s28, s36, 0x158000
	s_addc_u32 s29, s37, 0
	s_mov_b32 m0, s49
	ds_read_b128 v[186:189], v169 offset:32768
	ds_read_b128 v[190:193], v169 offset:33792
	ds_read_b128 v[194:197], v169 offset:34816
	ds_read_b128 v[198:201], v169 offset:35840
	ds_read_b128 v[202:205], v169 offset:36864
	ds_read_b128 v[206:209], v169 offset:37888
	ds_read_b128 v[210:213], v169 offset:38912
	ds_read_b128 v[214:217], v169 offset:39936
	global_load_lds_dwordx4 v152, s[28:29]
	s_mov_b32 m0, s50
	s_nop 0
	global_load_lds_dwordx4 v148, s[28:29]
	s_waitcnt vmcnt(8)
	s_waitcnt lgkmcnt(0)
	s_barrier
	s_setprio 1
	s_waitcnt lgkmcnt(0)
	v_mfma_i32_16x16x64_i8 v[126:129], v[130:133], v[186:189], v[126:129]
	v_mfma_i32_16x16x64_i8 v[122:125], v[138:141], v[186:189], v[122:125]
	v_mfma_i32_16x16x64_i8 v[110:113], v[130:133], v[194:197], v[110:113]
	v_mfma_i32_16x16x64_i8 v[106:109], v[138:141], v[194:197], v[106:109]
	v_mfma_i32_16x16x64_i8 v[94:97], v[130:133], v[202:205], v[94:97]
	v_mfma_i32_16x16x64_i8 v[90:93], v[138:141], v[202:205], v[90:93]
	v_mfma_i32_16x16x64_i8 v[78:81], v[130:133], v[210:213], v[78:81]
	v_mfma_i32_16x16x64_i8 v[74:77], v[138:141], v[210:213], v[74:77]
	v_mfma_i32_16x16x64_i8 v[126:129], v[134:137], v[190:193], v[126:129]
	v_mfma_i32_16x16x64_i8 v[122:125], v[142:145], v[190:193], v[122:125]
	v_mfma_i32_16x16x64_i8 v[110:113], v[134:137], v[198:201], v[110:113]
	v_mfma_i32_16x16x64_i8 v[106:109], v[142:145], v[198:201], v[106:109]
	v_mfma_i32_16x16x64_i8 v[94:97], v[134:137], v[206:209], v[94:97]
	v_mfma_i32_16x16x64_i8 v[90:93], v[142:145], v[206:209], v[90:93]
	v_mfma_i32_16x16x64_i8 v[78:81], v[134:137], v[214:217], v[78:81]
	v_mfma_i32_16x16x64_i8 v[74:77], v[142:145], v[214:217], v[74:77]
	s_setprio 0
	s_setprio 1
	v_mfma_i32_16x16x64_i8 v[118:121], v[170:173], v[186:189], v[118:121]
	v_mfma_i32_16x16x64_i8 v[114:117], v[178:181], v[186:189], v[114:117]
	v_mfma_i32_16x16x64_i8 v[102:105], v[170:173], v[194:197], v[102:105]
	v_mfma_i32_16x16x64_i8 v[98:101], v[178:181], v[194:197], v[98:101]
	v_mfma_i32_16x16x64_i8 v[86:89], v[170:173], v[202:205], v[86:89]
	v_mfma_i32_16x16x64_i8 v[82:85], v[178:181], v[202:205], v[82:85]
	v_mfma_i32_16x16x64_i8 v[70:73], v[170:173], v[210:213], v[70:73]
	v_mfma_i32_16x16x64_i8 v[66:69], v[178:181], v[210:213], v[66:69]
	v_mfma_i32_16x16x64_i8 v[118:121], v[174:177], v[190:193], v[118:121]
	v_mfma_i32_16x16x64_i8 v[114:117], v[182:185], v[190:193], v[114:117]
	v_mfma_i32_16x16x64_i8 v[102:105], v[174:177], v[198:201], v[102:105]
	v_mfma_i32_16x16x64_i8 v[98:101], v[182:185], v[198:201], v[98:101]
	v_mfma_i32_16x16x64_i8 v[86:89], v[174:177], v[206:209], v[86:89]
	v_mfma_i32_16x16x64_i8 v[82:85], v[182:185], v[206:209], v[82:85]
	v_mfma_i32_16x16x64_i8 v[70:73], v[174:177], v[214:217], v[70:73]
	v_mfma_i32_16x16x64_i8 v[66:69], v[182:185], v[214:217], v[66:69]
	s_setprio 0
	s_barrier
	s_add_i32 s28, s73, s46
	s_mov_b32 m0, s28
	ds_read_b128 v[186:189], v169 offset:49152
	ds_read_b128 v[190:193], v169 offset:50176
	ds_read_b128 v[194:197], v169 offset:51200
	ds_read_b128 v[198:201], v169 offset:52224
	ds_read_b128 v[202:205], v169 offset:53248
	ds_read_b128 v[206:209], v169 offset:54272
	ds_read_b128 v[210:213], v169 offset:55296
	ds_read_b128 v[214:217], v169 offset:56320
	global_load_lds_dwordx4 v150, s[98:99]
	s_add_i32 m0, s28, 0x2000
	s_add_u32 s28, s34, 0x158080
	s_addc_u32 s29, s35, 0
	s_add_i32 s34, s74, s46
	global_load_lds_dwordx4 v146, s[98:99]
	s_mov_b32 m0, s34
	s_nop 0
	global_load_lds_dwordx4 v150, s[28:29]
	s_add_i32 m0, s34, 0x2000
	s_nop 0
	global_load_lds_dwordx4 v146, s[28:29]
	s_mov_b32 m0, s54
	s_nop 0
	global_load_lds_dwordx4 v152, s[100:101]
	s_mov_b32 m0, s55
	s_nop 0
	global_load_lds_dwordx4 v148, s[100:101]
	s_waitcnt vmcnt(8)
	s_waitcnt lgkmcnt(0)
	s_barrier
	s_setprio 1
	s_waitcnt lgkmcnt(0)
	v_mfma_i32_16x16x64_i8 v[62:65], v[130:133], v[186:189], v[62:65]
	v_mfma_i32_16x16x64_i8 v[58:61], v[138:141], v[186:189], v[58:61]
	v_mfma_i32_16x16x64_i8 v[46:49], v[130:133], v[194:197], v[46:49]
	v_mfma_i32_16x16x64_i8 v[42:45], v[138:141], v[194:197], v[42:45]
	v_mfma_i32_16x16x64_i8 v[30:33], v[130:133], v[202:205], v[30:33]
	v_mfma_i32_16x16x64_i8 v[26:29], v[138:141], v[202:205], v[26:29]
	v_mfma_i32_16x16x64_i8 v[14:17], v[130:133], v[210:213], v[14:17]
	v_mfma_i32_16x16x64_i8 v[10:13], v[138:141], v[210:213], v[10:13]
	v_mfma_i32_16x16x64_i8 v[62:65], v[134:137], v[190:193], v[62:65]
	v_mfma_i32_16x16x64_i8 v[58:61], v[142:145], v[190:193], v[58:61]
	v_mfma_i32_16x16x64_i8 v[46:49], v[134:137], v[198:201], v[46:49]
	v_mfma_i32_16x16x64_i8 v[42:45], v[142:145], v[198:201], v[42:45]
	v_mfma_i32_16x16x64_i8 v[30:33], v[134:137], v[206:209], v[30:33]
	v_mfma_i32_16x16x64_i8 v[26:29], v[142:145], v[206:209], v[26:29]
	v_mfma_i32_16x16x64_i8 v[14:17], v[134:137], v[214:217], v[14:17]
	v_mfma_i32_16x16x64_i8 v[10:13], v[142:145], v[214:217], v[10:13]
	s_setprio 0
	s_setprio 1
	v_mfma_i32_16x16x64_i8 v[54:57], v[170:173], v[186:189], v[54:57]
	v_mfma_i32_16x16x64_i8 v[50:53], v[178:181], v[186:189], v[50:53]
	v_mfma_i32_16x16x64_i8 v[38:41], v[170:173], v[194:197], v[38:41]
	v_mfma_i32_16x16x64_i8 v[34:37], v[178:181], v[194:197], v[34:37]
	v_mfma_i32_16x16x64_i8 v[22:25], v[170:173], v[202:205], v[22:25]
	v_mfma_i32_16x16x64_i8 v[18:21], v[178:181], v[202:205], v[18:21]
	v_mfma_i32_16x16x64_i8 v[6:9], v[170:173], v[210:213], v[6:9]
	v_mfma_i32_16x16x64_i8 v[2:5], v[178:181], v[210:213], v[2:5]
	v_mfma_i32_16x16x64_i8 v[54:57], v[174:177], v[190:193], v[54:57]
	v_mfma_i32_16x16x64_i8 v[50:53], v[182:185], v[190:193], v[50:53]
	v_mfma_i32_16x16x64_i8 v[38:41], v[174:177], v[198:201], v[38:41]
	v_mfma_i32_16x16x64_i8 v[34:37], v[182:185], v[198:201], v[34:37]
	v_mfma_i32_16x16x64_i8 v[22:25], v[174:177], v[206:209], v[22:25]
	v_mfma_i32_16x16x64_i8 v[18:21], v[182:185], v[206:209], v[18:21]
	v_mfma_i32_16x16x64_i8 v[6:9], v[174:177], v[214:217], v[6:9]
	v_mfma_i32_16x16x64_i8 v[2:5], v[182:185], v[214:217], v[2:5]
	s_setprio 0
	s_barrier
	s_add_i32 s72, s72, 2
	s_add_u32 s70, s70, 0x100
	s_addc_u32 s71, s71, 0
	s_cmpk_gt_u32 s72, 0x53
	s_mov_b64 s[28:29], s[30:31]
	s_cbranch_scc0 .LBB0_1099
	s_and_b64 vcc, exec, s[16:17]
	s_cbranch_vccz .LBB0_1102
	s_barrier

.LBB0_1246:
	ds_read_b128 v[130:133], v193
	ds_read_b128 v[134:137], v193 offset:1024
	ds_read_b128 v[138:141], v193 offset:2048
	ds_read_b128 v[142:145], v193 offset:3072
	ds_read_b128 v[162:165], v194
	ds_read_b128 v[166:169], v194 offset:1024
	ds_read_b128 v[170:173], v194 offset:2048
	ds_read_b128 v[174:177], v194 offset:3072
	s_add_u32 s30, s28, 0xfff00080
	s_addc_u32 s31, s29, -1
	s_cmp_eq_u32 s68, 60
	s_cselect_b32 s35, s3, s31
	s_cselect_b32 s34, s23, s30
	s_cselect_b32 s31, s17, s65
	s_cselect_b32 s30, s62, s63
	s_add_i32 m0, s45, 0xc000
	ds_read_b128 v[178:181], v195
	ds_read_b128 v[182:185], v195 offset:1024
	ds_read_b128 v[186:189], v195 offset:2048
	ds_read_b128 v[196:199], v195 offset:3072
	ds_read_b128 v[200:203], v195 offset:4096
	ds_read_b128 v[204:207], v195 offset:5120
	ds_read_b128 v[208:211], v195 offset:6144
	ds_read_b128 v[212:215], v195 offset:7168
	global_load_lds_dwordx4 v154, s[28:29]
	s_add_i32 m0, s45, 0xe000
	s_nop 0
	global_load_lds_dwordx4 v156, s[28:29]
	s_waitcnt vmcnt(8)
	s_waitcnt lgkmcnt(0)
	s_barrier
	s_setprio 1
	s_waitcnt lgkmcnt(0)
	v_mfma_f32_16x16x32_bf16 v[126:129], v[130:133], v[178:181], v[126:129]
	v_mfma_f32_16x16x32_bf16 v[122:125], v[138:141], v[178:181], v[122:125]
	v_mfma_f32_16x16x32_bf16 v[118:121], v[130:133], v[186:189], v[118:121]
	v_mfma_f32_16x16x32_bf16 v[110:113], v[138:141], v[186:189], v[110:113]
	v_mfma_f32_16x16x32_bf16 v[98:101], v[130:133], v[200:203], v[98:101]
	v_mfma_f32_16x16x32_bf16 v[90:93], v[138:141], v[200:203], v[90:93]
	v_mfma_f32_16x16x32_bf16 v[82:85], v[130:133], v[208:211], v[82:85]
	v_mfma_f32_16x16x32_bf16 v[74:77], v[138:141], v[208:211], v[74:77]
	v_mfma_f32_16x16x32_bf16 v[126:129], v[134:137], v[182:185], v[126:129]
	v_mfma_f32_16x16x32_bf16 v[122:125], v[142:145], v[182:185], v[122:125]
	v_mfma_f32_16x16x32_bf16 v[118:121], v[134:137], v[196:199], v[118:121]
	v_mfma_f32_16x16x32_bf16 v[110:113], v[142:145], v[196:199], v[110:113]
	v_mfma_f32_16x16x32_bf16 v[98:101], v[134:137], v[204:207], v[98:101]
	v_mfma_f32_16x16x32_bf16 v[90:93], v[142:145], v[204:207], v[90:93]
	v_mfma_f32_16x16x32_bf16 v[82:85], v[134:137], v[212:215], v[82:85]
	v_mfma_f32_16x16x32_bf16 v[74:77], v[142:145], v[212:215], v[74:77]
	s_setprio 0
	s_setprio 1
	v_mfma_f32_16x16x32_bf16 v[114:117], v[162:165], v[178:181], v[114:117]
	v_mfma_f32_16x16x32_bf16 v[106:109], v[170:173], v[178:181], v[106:109]
	v_mfma_f32_16x16x32_bf16 v[102:105], v[162:165], v[186:189], v[102:105]
	v_mfma_f32_16x16x32_bf16 v[94:97], v[170:173], v[186:189], v[94:97]
	v_mfma_f32_16x16x32_bf16 v[86:89], v[162:165], v[200:203], v[86:89]
	v_mfma_f32_16x16x32_bf16 v[78:81], v[170:173], v[200:203], v[78:81]
	v_mfma_f32_16x16x32_bf16 v[70:73], v[162:165], v[208:211], v[70:73]
	v_mfma_f32_16x16x32_bf16 v[66:69], v[170:173], v[208:211], v[66:69]
	v_mfma_f32_16x16x32_bf16 v[114:117], v[166:169], v[182:185], v[114:117]
	v_mfma_f32_16x16x32_bf16 v[106:109], v[174:177], v[182:185], v[106:109]
	v_mfma_f32_16x16x32_bf16 v[102:105], v[166:169], v[196:199], v[102:105]
	v_mfma_f32_16x16x32_bf16 v[94:97], v[174:177], v[196:199], v[94:97]
	v_mfma_f32_16x16x32_bf16 v[86:89], v[166:169], v[204:207], v[86:89]
	v_mfma_f32_16x16x32_bf16 v[78:81], v[174:177], v[204:207], v[78:81]
	v_mfma_f32_16x16x32_bf16 v[70:73], v[166:169], v[212:215], v[70:73]
	v_mfma_f32_16x16x32_bf16 v[66:69], v[174:177], v[212:215], v[66:69]
	s_setprio 0
	s_barrier
	s_add_i32 s69, s58, s44
	s_add_u32 s98, s30, s12
	s_addc_u32 s99, s31, s13
	s_mov_b32 m0, s69
	ds_read_b128 v[178:181], v195 offset:16384
	ds_read_b128 v[182:185], v195 offset:17408
	ds_read_b128 v[186:189], v195 offset:18432
	ds_read_b128 v[196:199], v195 offset:19456
	ds_read_b128 v[200:203], v195 offset:20480
	ds_read_b128 v[204:207], v195 offset:21504
	ds_read_b128 v[208:211], v195 offset:22528
	ds_read_b128 v[212:215], v195 offset:23552
	global_load_lds_dwordx4 v148, s[30:31]
	s_add_i32 m0, s69, 0x2000
	s_add_u32 s70, s30, 0x100000
	s_addc_u32 s71, s31, 0
	s_add_i32 s69, s59, s44
	global_load_lds_dwordx4 v152, s[30:31]
	s_mov_b32 m0, s69
	s_nop 0
	global_load_lds_dwordx4 v148, s[70:71]
	s_add_i32 m0, s69, 0x2000
	s_nop 0
	global_load_lds_dwordx4 v152, s[70:71]
	s_add_u32 s100, s34, s12
	s_addc_u32 s101, s35, s13
	s_mov_b32 m0, s45
	s_nop 0
	global_load_lds_dwordx4 v146, s[34:35]
	s_mov_b32 m0, s46
	s_nop 0
	global_load_lds_dwordx4 v150, s[34:35]
	s_waitcnt vmcnt(8)
	s_waitcnt lgkmcnt(0)
	s_barrier
	s_setprio 1
	s_waitcnt lgkmcnt(0)
	v_mfma_f32_16x16x32_bf16 v[62:65], v[130:133], v[178:181], v[62:65]
	v_mfma_f32_16x16x32_bf16 v[58:61], v[138:141], v[178:181], v[58:61]
	v_mfma_f32_16x16x32_bf16 v[46:49], v[130:133], v[186:189], v[46:49]
	v_mfma_f32_16x16x32_bf16 v[42:45], v[138:141], v[186:189], v[42:45]
	v_mfma_f32_16x16x32_bf16 v[30:33], v[130:133], v[200:203], v[30:33]
	v_mfma_f32_16x16x32_bf16 v[26:29], v[138:141], v[200:203], v[26:29]
	v_mfma_f32_16x16x32_bf16 v[14:17], v[130:133], v[208:211], v[14:17]
	v_mfma_f32_16x16x32_bf16 v[10:13], v[138:141], v[208:211], v[10:13]
	v_mfma_f32_16x16x32_bf16 v[62:65], v[134:137], v[182:185], v[62:65]
	v_mfma_f32_16x16x32_bf16 v[58:61], v[142:145], v[182:185], v[58:61]
	v_mfma_f32_16x16x32_bf16 v[46:49], v[134:137], v[196:199], v[46:49]
	v_mfma_f32_16x16x32_bf16 v[42:45], v[142:145], v[196:199], v[42:45]
	v_mfma_f32_16x16x32_bf16 v[30:33], v[134:137], v[204:207], v[30:33]
	v_mfma_f32_16x16x32_bf16 v[26:29], v[142:145], v[204:207], v[26:29]
	v_mfma_f32_16x16x32_bf16 v[14:17], v[134:137], v[212:215], v[14:17]
	v_mfma_f32_16x16x32_bf16 v[10:13], v[142:145], v[212:215], v[10:13]
	s_setprio 0
	s_setprio 1
	v_mfma_f32_16x16x32_bf16 v[54:57], v[162:165], v[178:181], v[54:57]
	v_mfma_f32_16x16x32_bf16 v[50:53], v[170:173], v[178:181], v[50:53]
	v_mfma_f32_16x16x32_bf16 v[38:41], v[162:165], v[186:189], v[38:41]
	v_mfma_f32_16x16x32_bf16 v[34:37], v[170:173], v[186:189], v[34:37]
	v_mfma_f32_16x16x32_bf16 v[22:25], v[162:165], v[200:203], v[22:25]
	v_mfma_f32_16x16x32_bf16 v[18:21], v[170:173], v[200:203], v[18:21]
	v_mfma_f32_16x16x32_bf16 v[6:9], v[162:165], v[208:211], v[6:9]
	v_mfma_f32_16x16x32_bf16 v[2:5], v[170:173], v[208:211], v[2:5]
	v_mfma_f32_16x16x32_bf16 v[54:57], v[166:169], v[182:185], v[54:57]
	v_mfma_f32_16x16x32_bf16 v[50:53], v[174:177], v[182:185], v[50:53]
	v_mfma_f32_16x16x32_bf16 v[38:41], v[166:169], v[196:199], v[38:41]
	v_mfma_f32_16x16x32_bf16 v[34:37], v[174:177], v[196:199], v[34:37]
	v_mfma_f32_16x16x32_bf16 v[22:25], v[166:169], v[204:207], v[22:25]
	v_mfma_f32_16x16x32_bf16 v[18:21], v[174:177], v[204:207], v[18:21]
	v_mfma_f32_16x16x32_bf16 v[6:9], v[166:169], v[212:215], v[6:9]
	v_mfma_f32_16x16x32_bf16 v[2:5], v[174:177], v[212:215], v[2:5]
	s_setprio 0
	s_barrier
	s_add_i32 s69, 0, 0x18000
	s_add_i32 s70, 0, 0x1c000
	v_add_u32_e32 v142, s69, v192
	v_add_u32_e32 v174, s70, v192
	ds_read_b128 v[130:133], v142
	ds_read_b128 v[134:137], v142 offset:1024
	ds_read_b128 v[138:141], v142 offset:2048
	ds_read_b128 v[142:145], v142 offset:3072
	ds_read_b128 v[162:165], v174
	ds_read_b128 v[166:169], v174 offset:1024
	ds_read_b128 v[170:173], v174 offset:2048
	ds_read_b128 v[174:177], v174 offset:3072
	s_add_u32 s34, s34, 0x100000
	s_addc_u32 s35, s35, 0
	s_mov_b32 m0, s47
	ds_read_b128 v[178:181], v195 offset:32768
	ds_read_b128 v[182:185], v195 offset:33792
	ds_read_b128 v[186:189], v195 offset:34816
	ds_read_b128 v[196:199], v195 offset:35840
	ds_read_b128 v[200:203], v195 offset:36864
	ds_read_b128 v[204:207], v195 offset:37888
	ds_read_b128 v[208:211], v195 offset:38912
	ds_read_b128 v[212:215], v195 offset:39936
	global_load_lds_dwordx4 v146, s[34:35]
	s_mov_b32 m0, s48
	s_nop 0
	global_load_lds_dwordx4 v150, s[34:35]
	s_waitcnt vmcnt(8)
	s_waitcnt lgkmcnt(0)
	s_barrier
	s_setprio 1
	s_waitcnt lgkmcnt(0)
	v_mfma_f32_16x16x32_bf16 v[126:129], v[130:133], v[178:181], v[126:129]
	v_mfma_f32_16x16x32_bf16 v[122:125], v[138:141], v[178:181], v[122:125]
	v_mfma_f32_16x16x32_bf16 v[118:121], v[130:133], v[186:189], v[118:121]
	v_mfma_f32_16x16x32_bf16 v[110:113], v[138:141], v[186:189], v[110:113]
	v_mfma_f32_16x16x32_bf16 v[98:101], v[130:133], v[200:203], v[98:101]
	v_mfma_f32_16x16x32_bf16 v[90:93], v[138:141], v[200:203], v[90:93]
	v_mfma_f32_16x16x32_bf16 v[82:85], v[130:133], v[208:211], v[82:85]
	v_mfma_f32_16x16x32_bf16 v[74:77], v[138:141], v[208:211], v[74:77]
	v_mfma_f32_16x16x32_bf16 v[126:129], v[134:137], v[182:185], v[126:129]
	v_mfma_f32_16x16x32_bf16 v[122:125], v[142:145], v[182:185], v[122:125]
	v_mfma_f32_16x16x32_bf16 v[118:121], v[134:137], v[196:199], v[118:121]
	v_mfma_f32_16x16x32_bf16 v[110:113], v[142:145], v[196:199], v[110:113]
	v_mfma_f32_16x16x32_bf16 v[98:101], v[134:137], v[204:207], v[98:101]
	v_mfma_f32_16x16x32_bf16 v[90:93], v[142:145], v[204:207], v[90:93]
	v_mfma_f32_16x16x32_bf16 v[82:85], v[134:137], v[212:215], v[82:85]
	v_mfma_f32_16x16x32_bf16 v[74:77], v[142:145], v[212:215], v[74:77]
	s_setprio 0
	s_setprio 1
	v_mfma_f32_16x16x32_bf16 v[114:117], v[162:165], v[178:181], v[114:117]
	v_mfma_f32_16x16x32_bf16 v[106:109], v[170:173], v[178:181], v[106:109]
	v_mfma_f32_16x16x32_bf16 v[102:105], v[162:165], v[186:189], v[102:105]
	v_mfma_f32_16x16x32_bf16 v[94:97], v[170:173], v[186:189], v[94:97]
	v_mfma_f32_16x16x32_bf16 v[86:89], v[162:165], v[200:203], v[86:89]
	v_mfma_f32_16x16x32_bf16 v[78:81], v[170:173], v[200:203], v[78:81]
	v_mfma_f32_16x16x32_bf16 v[70:73], v[162:165], v[208:211], v[70:73]
	v_mfma_f32_16x16x32_bf16 v[66:69], v[170:173], v[208:211], v[66:69]
	v_mfma_f32_16x16x32_bf16 v[114:117], v[166:169], v[182:185], v[114:117]
	v_mfma_f32_16x16x32_bf16 v[106:109], v[174:177], v[182:185], v[106:109]
	v_mfma_f32_16x16x32_bf16 v[102:105], v[166:169], v[196:199], v[102:105]
	v_mfma_f32_16x16x32_bf16 v[94:97], v[174:177], v[196:199], v[94:97]
	v_mfma_f32_16x16x32_bf16 v[86:89], v[166:169], v[204:207], v[86:89]
	v_mfma_f32_16x16x32_bf16 v[78:81], v[174:177], v[204:207], v[78:81]
	v_mfma_f32_16x16x32_bf16 v[70:73], v[166:169], v[212:215], v[70:73]
	v_mfma_f32_16x16x32_bf16 v[66:69], v[174:177], v[212:215], v[66:69]
	s_setprio 0
	s_barrier
	s_add_i32 s34, s69, s44
	s_mov_b32 m0, s34
	ds_read_b128 v[178:181], v195 offset:49152
	ds_read_b128 v[182:185], v195 offset:50176
	ds_read_b128 v[186:189], v195 offset:51200
	ds_read_b128 v[196:199], v195 offset:52224
	ds_read_b128 v[200:203], v195 offset:53248
	ds_read_b128 v[204:207], v195 offset:54272
	ds_read_b128 v[208:211], v195 offset:55296
	ds_read_b128 v[212:215], v195 offset:56320
	global_load_lds_dwordx4 v148, s[98:99]
	s_add_i32 m0, s34, 0x2000
	s_add_u32 s30, s30, 0x100080
	s_addc_u32 s31, s31, 0
	s_add_i32 s34, s70, s44
	global_load_lds_dwordx4 v152, s[98:99]
	s_mov_b32 m0, s34
	s_nop 0
	global_load_lds_dwordx4 v148, s[30:31]
	s_add_i32 m0, s34, 0x2000
	s_nop 0
	global_load_lds_dwordx4 v152, s[30:31]
	s_mov_b32 m0, s55
	s_nop 0
	global_load_lds_dwordx4 v146, s[100:101]
	s_mov_b32 m0, s56
	s_nop 0
	global_load_lds_dwordx4 v150, s[100:101]
	s_waitcnt vmcnt(8)
	s_waitcnt lgkmcnt(0)
	s_barrier
	s_setprio 1
	s_waitcnt lgkmcnt(0)
	v_mfma_f32_16x16x32_bf16 v[62:65], v[130:133], v[178:181], v[62:65]
	v_mfma_f32_16x16x32_bf16 v[58:61], v[138:141], v[178:181], v[58:61]
	v_mfma_f32_16x16x32_bf16 v[46:49], v[130:133], v[186:189], v[46:49]
	v_mfma_f32_16x16x32_bf16 v[42:45], v[138:141], v[186:189], v[42:45]
	v_mfma_f32_16x16x32_bf16 v[30:33], v[130:133], v[200:203], v[30:33]
	v_mfma_f32_16x16x32_bf16 v[26:29], v[138:141], v[200:203], v[26:29]
	v_mfma_f32_16x16x32_bf16 v[14:17], v[130:133], v[208:211], v[14:17]
	v_mfma_f32_16x16x32_bf16 v[10:13], v[138:141], v[208:211], v[10:13]
	v_mfma_f32_16x16x32_bf16 v[62:65], v[134:137], v[182:185], v[62:65]
	v_mfma_f32_16x16x32_bf16 v[58:61], v[142:145], v[182:185], v[58:61]
	v_mfma_f32_16x16x32_bf16 v[46:49], v[134:137], v[196:199], v[46:49]
	v_mfma_f32_16x16x32_bf16 v[42:45], v[142:145], v[196:199], v[42:45]
	v_mfma_f32_16x16x32_bf16 v[30:33], v[134:137], v[204:207], v[30:33]
	v_mfma_f32_16x16x32_bf16 v[26:29], v[142:145], v[204:207], v[26:29]
	v_mfma_f32_16x16x32_bf16 v[14:17], v[134:137], v[212:215], v[14:17]
	v_mfma_f32_16x16x32_bf16 v[10:13], v[142:145], v[212:215], v[10:13]
	s_setprio 0
	s_setprio 1
	v_mfma_f32_16x16x32_bf16 v[54:57], v[162:165], v[178:181], v[54:57]
	v_mfma_f32_16x16x32_bf16 v[50:53], v[170:173], v[178:181], v[50:53]
	v_mfma_f32_16x16x32_bf16 v[38:41], v[162:165], v[186:189], v[38:41]
	v_mfma_f32_16x16x32_bf16 v[34:37], v[170:173], v[186:189], v[34:37]
	v_mfma_f32_16x16x32_bf16 v[22:25], v[162:165], v[200:203], v[22:25]
	v_mfma_f32_16x16x32_bf16 v[18:21], v[170:173], v[200:203], v[18:21]
	v_mfma_f32_16x16x32_bf16 v[6:9], v[162:165], v[208:211], v[6:9]
	v_mfma_f32_16x16x32_bf16 v[2:5], v[170:173], v[208:211], v[2:5]
	v_mfma_f32_16x16x32_bf16 v[54:57], v[166:169], v[182:185], v[54:57]
	v_mfma_f32_16x16x32_bf16 v[50:53], v[174:177], v[182:185], v[50:53]
	v_mfma_f32_16x16x32_bf16 v[38:41], v[166:169], v[196:199], v[38:41]
	v_mfma_f32_16x16x32_bf16 v[34:37], v[174:177], v[196:199], v[34:37]
	v_mfma_f32_16x16x32_bf16 v[22:25], v[166:169], v[204:207], v[22:25]
	v_mfma_f32_16x16x32_bf16 v[18:21], v[174:177], v[204:207], v[18:21]
	v_mfma_f32_16x16x32_bf16 v[6:9], v[166:169], v[212:215], v[6:9]
	v_mfma_f32_16x16x32_bf16 v[2:5], v[174:177], v[212:215], v[2:5]
	s_setprio 0
	s_barrier
	s_add_i32 s68, s68, 2
	s_add_u32 s28, s28, 0x100
	s_addc_u32 s29, s29, 0
	s_add_u32 s63, s63, 0x100
	s_addc_u32 s65, s65, 0
	s_cmp_gt_u32 s68, 61
	s_cbranch_scc0 .LBB0_1246
	s_and_b64 vcc, exec, s[14:15]
	s_cbranch_vccz .LBB0_1249
	s_barrier

.LBB0_1521:
	ds_read_b128 v[130:133], v169
	ds_read_b128 v[134:137], v169 offset:1024
	ds_read_b128 v[138:141], v169 offset:2048
	ds_read_b128 v[142:145], v169 offset:3072
	ds_read_b128 v[162:165], v170
	ds_read_b128 v[172:175], v170 offset:1024
	ds_read_b128 v[176:179], v170 offset:2048
	ds_read_b128 v[180:183], v170 offset:3072
	s_add_u32 s38, s2, 0xfff00080
	s_addc_u32 s39, s3, -1
	s_cmp_eq_u32 s69, 60
	s_cselect_b32 s45, s29, s39
	s_cselect_b32 s44, s65, s38
	s_cselect_b32 s39, s27, s68
	s_cselect_b32 s38, s66, s67
	s_add_i32 m0, s37, 0xc000
	ds_read_b128 v[184:187], v171
	ds_read_b128 v[188:191], v171 offset:1024
	ds_read_b128 v[192:195], v171 offset:2048
	ds_read_b128 v[196:199], v171 offset:3072
	ds_read_b128 v[200:203], v171 offset:4096
	ds_read_b128 v[204:207], v171 offset:5120
	ds_read_b128 v[208:211], v171 offset:6144
	ds_read_b128 v[212:215], v171 offset:7168
	global_load_lds_dwordx4 v154, s[2:3]
	s_add_i32 m0, s37, 0xe000
	s_nop 0
	global_load_lds_dwordx4 v156, s[2:3]
	s_waitcnt vmcnt(8)
	s_waitcnt lgkmcnt(0)
	s_barrier
	s_setprio 1
	s_waitcnt lgkmcnt(0)
	v_mfma_f32_16x16x32_bf16 v[126:129], v[130:133], v[184:187], v[126:129]
	v_mfma_f32_16x16x32_bf16 v[122:125], v[138:141], v[184:187], v[122:125]
	v_mfma_f32_16x16x32_bf16 v[114:117], v[130:133], v[192:195], v[114:117]
	v_mfma_f32_16x16x32_bf16 v[106:109], v[138:141], v[192:195], v[106:109]
	v_mfma_f32_16x16x32_bf16 v[98:101], v[130:133], v[200:203], v[98:101]
	v_mfma_f32_16x16x32_bf16 v[90:93], v[138:141], v[200:203], v[90:93]
	v_mfma_f32_16x16x32_bf16 v[82:85], v[130:133], v[208:211], v[82:85]
	v_mfma_f32_16x16x32_bf16 v[74:77], v[138:141], v[208:211], v[74:77]
	v_mfma_f32_16x16x32_bf16 v[126:129], v[134:137], v[188:191], v[126:129]
	v_mfma_f32_16x16x32_bf16 v[122:125], v[142:145], v[188:191], v[122:125]
	v_mfma_f32_16x16x32_bf16 v[114:117], v[134:137], v[196:199], v[114:117]
	v_mfma_f32_16x16x32_bf16 v[106:109], v[142:145], v[196:199], v[106:109]
	v_mfma_f32_16x16x32_bf16 v[98:101], v[134:137], v[204:207], v[98:101]
	v_mfma_f32_16x16x32_bf16 v[90:93], v[142:145], v[204:207], v[90:93]
	v_mfma_f32_16x16x32_bf16 v[82:85], v[134:137], v[212:215], v[82:85]
	v_mfma_f32_16x16x32_bf16 v[74:77], v[142:145], v[212:215], v[74:77]
	s_setprio 0
	s_setprio 1
	v_mfma_f32_16x16x32_bf16 v[118:121], v[162:165], v[184:187], v[118:121]
	v_mfma_f32_16x16x32_bf16 v[110:113], v[176:179], v[184:187], v[110:113]
	v_mfma_f32_16x16x32_bf16 v[102:105], v[162:165], v[192:195], v[102:105]
	v_mfma_f32_16x16x32_bf16 v[94:97], v[176:179], v[192:195], v[94:97]
	v_mfma_f32_16x16x32_bf16 v[86:89], v[162:165], v[200:203], v[86:89]
	v_mfma_f32_16x16x32_bf16 v[78:81], v[176:179], v[200:203], v[78:81]
	v_mfma_f32_16x16x32_bf16 v[70:73], v[162:165], v[208:211], v[70:73]
	v_mfma_f32_16x16x32_bf16 v[66:69], v[176:179], v[208:211], v[66:69]
	v_mfma_f32_16x16x32_bf16 v[118:121], v[172:175], v[188:191], v[118:121]
	v_mfma_f32_16x16x32_bf16 v[110:113], v[180:183], v[188:191], v[110:113]
	v_mfma_f32_16x16x32_bf16 v[102:105], v[172:175], v[196:199], v[102:105]
	v_mfma_f32_16x16x32_bf16 v[94:97], v[180:183], v[196:199], v[94:97]
	v_mfma_f32_16x16x32_bf16 v[86:89], v[172:175], v[204:207], v[86:89]
	v_mfma_f32_16x16x32_bf16 v[78:81], v[180:183], v[204:207], v[78:81]
	v_mfma_f32_16x16x32_bf16 v[70:73], v[172:175], v[212:215], v[70:73]
	v_mfma_f32_16x16x32_bf16 v[66:69], v[180:183], v[212:215], v[66:69]
	s_setprio 0
	s_barrier
	s_add_i32 s43, s57, s50
	s_add_u32 s98, s38, s16
	s_addc_u32 s99, s39, s17
	s_mov_b32 m0, s43
	ds_read_b128 v[184:187], v171 offset:16384
	ds_read_b128 v[188:191], v171 offset:17408
	ds_read_b128 v[192:195], v171 offset:18432
	ds_read_b128 v[196:199], v171 offset:19456
	ds_read_b128 v[200:203], v171 offset:20480
	ds_read_b128 v[204:207], v171 offset:21504
	ds_read_b128 v[208:211], v171 offset:22528
	ds_read_b128 v[212:215], v171 offset:23552
	global_load_lds_dwordx4 v150, s[38:39]
	s_add_i32 m0, s43, 0x2000
	s_add_u32 s70, s38, 0x100000
	s_addc_u32 s71, s39, 0
	s_add_i32 s43, s58, s50
	global_load_lds_dwordx4 v146, s[38:39]
	s_mov_b32 m0, s43
	s_nop 0
	global_load_lds_dwordx4 v150, s[70:71]
	s_add_i32 m0, s43, 0x2000
	s_nop 0
	global_load_lds_dwordx4 v146, s[70:71]
	s_add_u32 s100, s44, s16
	s_addc_u32 s101, s45, s17
	s_mov_b32 m0, s37
	s_nop 0
	global_load_lds_dwordx4 v152, s[44:45]
	s_mov_b32 m0, s51
	s_nop 0
	global_load_lds_dwordx4 v148, s[44:45]
	s_waitcnt vmcnt(8)
	s_waitcnt lgkmcnt(0)
	s_barrier
	s_setprio 1
	s_waitcnt lgkmcnt(0)
	v_mfma_f32_16x16x32_bf16 v[62:65], v[130:133], v[184:187], v[62:65]
	v_mfma_f32_16x16x32_bf16 v[58:61], v[138:141], v[184:187], v[58:61]
	v_mfma_f32_16x16x32_bf16 v[50:53], v[130:133], v[192:195], v[50:53]
	v_mfma_f32_16x16x32_bf16 v[42:45], v[138:141], v[192:195], v[42:45]
	v_mfma_f32_16x16x32_bf16 v[34:37], v[130:133], v[200:203], v[34:37]
	v_mfma_f32_16x16x32_bf16 v[26:29], v[138:141], v[200:203], v[26:29]
	v_mfma_f32_16x16x32_bf16 v[18:21], v[130:133], v[208:211], v[18:21]
	v_mfma_f32_16x16x32_bf16 v[10:13], v[138:141], v[208:211], v[10:13]
	v_mfma_f32_16x16x32_bf16 v[62:65], v[134:137], v[188:191], v[62:65]
	v_mfma_f32_16x16x32_bf16 v[58:61], v[142:145], v[188:191], v[58:61]
	v_mfma_f32_16x16x32_bf16 v[50:53], v[134:137], v[196:199], v[50:53]
	v_mfma_f32_16x16x32_bf16 v[42:45], v[142:145], v[196:199], v[42:45]
	v_mfma_f32_16x16x32_bf16 v[34:37], v[134:137], v[204:207], v[34:37]
	v_mfma_f32_16x16x32_bf16 v[26:29], v[142:145], v[204:207], v[26:29]
	v_mfma_f32_16x16x32_bf16 v[18:21], v[134:137], v[212:215], v[18:21]
	v_mfma_f32_16x16x32_bf16 v[10:13], v[142:145], v[212:215], v[10:13]
	s_setprio 0
	s_setprio 1
	v_mfma_f32_16x16x32_bf16 v[54:57], v[162:165], v[184:187], v[54:57]
	v_mfma_f32_16x16x32_bf16 v[46:49], v[176:179], v[184:187], v[46:49]
	v_mfma_f32_16x16x32_bf16 v[38:41], v[162:165], v[192:195], v[38:41]
	v_mfma_f32_16x16x32_bf16 v[30:33], v[176:179], v[192:195], v[30:33]
	v_mfma_f32_16x16x32_bf16 v[22:25], v[162:165], v[200:203], v[22:25]
	v_mfma_f32_16x16x32_bf16 v[14:17], v[176:179], v[200:203], v[14:17]
	v_mfma_f32_16x16x32_bf16 v[6:9], v[162:165], v[208:211], v[6:9]
	v_mfma_f32_16x16x32_bf16 v[2:5], v[176:179], v[208:211], v[2:5]
	v_mfma_f32_16x16x32_bf16 v[54:57], v[172:175], v[188:191], v[54:57]
	v_mfma_f32_16x16x32_bf16 v[46:49], v[180:183], v[188:191], v[46:49]
	v_mfma_f32_16x16x32_bf16 v[38:41], v[172:175], v[196:199], v[38:41]
	v_mfma_f32_16x16x32_bf16 v[30:33], v[180:183], v[196:199], v[30:33]
	v_mfma_f32_16x16x32_bf16 v[22:25], v[172:175], v[204:207], v[22:25]
	v_mfma_f32_16x16x32_bf16 v[14:17], v[180:183], v[204:207], v[14:17]
	v_mfma_f32_16x16x32_bf16 v[6:9], v[172:175], v[212:215], v[6:9]
	v_mfma_f32_16x16x32_bf16 v[2:5], v[180:183], v[212:215], v[2:5]
	s_setprio 0
	s_barrier
	s_add_i32 s43, 0, 0x18000
	s_add_i32 s70, 0, 0x1c000
	v_add_u32_e32 v142, s43, v167
	v_add_u32_e32 v180, s70, v167
	ds_read_b128 v[130:133], v142
	ds_read_b128 v[134:137], v142 offset:1024
	ds_read_b128 v[138:141], v142 offset:2048
	ds_read_b128 v[142:145], v142 offset:3072
	ds_read_b128 v[162:165], v180
	ds_read_b128 v[172:175], v180 offset:1024
	ds_read_b128 v[176:179], v180 offset:2048
	ds_read_b128 v[180:183], v180 offset:3072
	s_add_u32 s44, s44, 0x100000
	s_addc_u32 s45, s45, 0
	s_mov_b32 m0, s52
	ds_read_b128 v[184:187], v171 offset:32768
	ds_read_b128 v[188:191], v171 offset:33792
	ds_read_b128 v[192:195], v171 offset:34816
	ds_read_b128 v[196:199], v171 offset:35840
	ds_read_b128 v[200:203], v171 offset:36864
	ds_read_b128 v[204:207], v171 offset:37888
	ds_read_b128 v[208:211], v171 offset:38912
	ds_read_b128 v[212:215], v171 offset:39936
	global_load_lds_dwordx4 v152, s[44:45]
	s_mov_b32 m0, s53
	s_nop 0
	global_load_lds_dwordx4 v148, s[44:45]
	s_waitcnt vmcnt(8)
	s_waitcnt lgkmcnt(0)
	s_barrier
	s_setprio 1
	s_waitcnt lgkmcnt(0)
	v_mfma_f32_16x16x32_bf16 v[126:129], v[130:133], v[184:187], v[126:129]
	v_mfma_f32_16x16x32_bf16 v[122:125], v[138:141], v[184:187], v[122:125]
	v_mfma_f32_16x16x32_bf16 v[114:117], v[130:133], v[192:195], v[114:117]
	v_mfma_f32_16x16x32_bf16 v[106:109], v[138:141], v[192:195], v[106:109]
	v_mfma_f32_16x16x32_bf16 v[98:101], v[130:133], v[200:203], v[98:101]
	v_mfma_f32_16x16x32_bf16 v[90:93], v[138:141], v[200:203], v[90:93]
	v_mfma_f32_16x16x32_bf16 v[82:85], v[130:133], v[208:211], v[82:85]
	v_mfma_f32_16x16x32_bf16 v[74:77], v[138:141], v[208:211], v[74:77]
	v_mfma_f32_16x16x32_bf16 v[126:129], v[134:137], v[188:191], v[126:129]
	v_mfma_f32_16x16x32_bf16 v[122:125], v[142:145], v[188:191], v[122:125]
	v_mfma_f32_16x16x32_bf16 v[114:117], v[134:137], v[196:199], v[114:117]
	v_mfma_f32_16x16x32_bf16 v[106:109], v[142:145], v[196:199], v[106:109]
	v_mfma_f32_16x16x32_bf16 v[98:101], v[134:137], v[204:207], v[98:101]
	v_mfma_f32_16x16x32_bf16 v[90:93], v[142:145], v[204:207], v[90:93]
	v_mfma_f32_16x16x32_bf16 v[82:85], v[134:137], v[212:215], v[82:85]
	v_mfma_f32_16x16x32_bf16 v[74:77], v[142:145], v[212:215], v[74:77]
	s_setprio 0
	s_setprio 1
	v_mfma_f32_16x16x32_bf16 v[118:121], v[162:165], v[184:187], v[118:121]
	v_mfma_f32_16x16x32_bf16 v[110:113], v[176:179], v[184:187], v[110:113]
	v_mfma_f32_16x16x32_bf16 v[102:105], v[162:165], v[192:195], v[102:105]
	v_mfma_f32_16x16x32_bf16 v[94:97], v[176:179], v[192:195], v[94:97]
	v_mfma_f32_16x16x32_bf16 v[86:89], v[162:165], v[200:203], v[86:89]
	v_mfma_f32_16x16x32_bf16 v[78:81], v[176:179], v[200:203], v[78:81]
	v_mfma_f32_16x16x32_bf16 v[70:73], v[162:165], v[208:211], v[70:73]
	v_mfma_f32_16x16x32_bf16 v[66:69], v[176:179], v[208:211], v[66:69]
	v_mfma_f32_16x16x32_bf16 v[118:121], v[172:175], v[188:191], v[118:121]
	v_mfma_f32_16x16x32_bf16 v[110:113], v[180:183], v[188:191], v[110:113]
	v_mfma_f32_16x16x32_bf16 v[102:105], v[172:175], v[196:199], v[102:105]
	v_mfma_f32_16x16x32_bf16 v[94:97], v[180:183], v[196:199], v[94:97]
	v_mfma_f32_16x16x32_bf16 v[86:89], v[172:175], v[204:207], v[86:89]
	v_mfma_f32_16x16x32_bf16 v[78:81], v[180:183], v[204:207], v[78:81]
	v_mfma_f32_16x16x32_bf16 v[70:73], v[172:175], v[212:215], v[70:73]
	v_mfma_f32_16x16x32_bf16 v[66:69], v[180:183], v[212:215], v[66:69]
	s_setprio 0
	s_barrier
	s_add_i32 s43, s43, s50
	s_mov_b32 m0, s43
	ds_read_b128 v[184:187], v171 offset:49152
	ds_read_b128 v[188:191], v171 offset:50176
	ds_read_b128 v[192:195], v171 offset:51200
	ds_read_b128 v[196:199], v171 offset:52224
	ds_read_b128 v[200:203], v171 offset:53248
	ds_read_b128 v[204:207], v171 offset:54272
	ds_read_b128 v[208:211], v171 offset:55296
	ds_read_b128 v[212:215], v171 offset:56320
	global_load_lds_dwordx4 v150, s[98:99]
	s_add_i32 m0, s43, 0x2000
	s_add_u32 s38, s38, 0x100080
	s_addc_u32 s39, s39, 0
	s_add_i32 s43, s70, s50
	global_load_lds_dwordx4 v146, s[98:99]
	s_mov_b32 m0, s43
	s_nop 0
	global_load_lds_dwordx4 v150, s[38:39]
	s_add_i32 m0, s43, 0x2000
	s_nop 0
	global_load_lds_dwordx4 v146, s[38:39]
	s_mov_b32 m0, s55
	s_nop 0
	global_load_lds_dwordx4 v152, s[100:101]
	s_mov_b32 m0, s56
	s_nop 0
	global_load_lds_dwordx4 v148, s[100:101]
	s_waitcnt vmcnt(8)
	s_waitcnt lgkmcnt(0)
	s_barrier
	s_setprio 1
	s_waitcnt lgkmcnt(0)
	v_mfma_f32_16x16x32_bf16 v[62:65], v[130:133], v[184:187], v[62:65]
	v_mfma_f32_16x16x32_bf16 v[58:61], v[138:141], v[184:187], v[58:61]
	v_mfma_f32_16x16x32_bf16 v[50:53], v[130:133], v[192:195], v[50:53]
	v_mfma_f32_16x16x32_bf16 v[42:45], v[138:141], v[192:195], v[42:45]
	v_mfma_f32_16x16x32_bf16 v[34:37], v[130:133], v[200:203], v[34:37]
	v_mfma_f32_16x16x32_bf16 v[26:29], v[138:141], v[200:203], v[26:29]
	v_mfma_f32_16x16x32_bf16 v[18:21], v[130:133], v[208:211], v[18:21]
	v_mfma_f32_16x16x32_bf16 v[10:13], v[138:141], v[208:211], v[10:13]
	v_mfma_f32_16x16x32_bf16 v[62:65], v[134:137], v[188:191], v[62:65]
	v_mfma_f32_16x16x32_bf16 v[58:61], v[142:145], v[188:191], v[58:61]
	v_mfma_f32_16x16x32_bf16 v[50:53], v[134:137], v[196:199], v[50:53]
	v_mfma_f32_16x16x32_bf16 v[42:45], v[142:145], v[196:199], v[42:45]
	v_mfma_f32_16x16x32_bf16 v[34:37], v[134:137], v[204:207], v[34:37]
	v_mfma_f32_16x16x32_bf16 v[26:29], v[142:145], v[204:207], v[26:29]
	v_mfma_f32_16x16x32_bf16 v[18:21], v[134:137], v[212:215], v[18:21]
	v_mfma_f32_16x16x32_bf16 v[10:13], v[142:145], v[212:215], v[10:13]
	s_setprio 0
	s_setprio 1
	v_mfma_f32_16x16x32_bf16 v[54:57], v[162:165], v[184:187], v[54:57]
	v_mfma_f32_16x16x32_bf16 v[46:49], v[176:179], v[184:187], v[46:49]
	v_mfma_f32_16x16x32_bf16 v[38:41], v[162:165], v[192:195], v[38:41]
	v_mfma_f32_16x16x32_bf16 v[30:33], v[176:179], v[192:195], v[30:33]
	v_mfma_f32_16x16x32_bf16 v[22:25], v[162:165], v[200:203], v[22:25]
	v_mfma_f32_16x16x32_bf16 v[14:17], v[176:179], v[200:203], v[14:17]
	v_mfma_f32_16x16x32_bf16 v[6:9], v[162:165], v[208:211], v[6:9]
	v_mfma_f32_16x16x32_bf16 v[2:5], v[176:179], v[208:211], v[2:5]
	v_mfma_f32_16x16x32_bf16 v[54:57], v[172:175], v[188:191], v[54:57]
	v_mfma_f32_16x16x32_bf16 v[46:49], v[180:183], v[188:191], v[46:49]
	v_mfma_f32_16x16x32_bf16 v[38:41], v[172:175], v[196:199], v[38:41]
	v_mfma_f32_16x16x32_bf16 v[30:33], v[180:183], v[196:199], v[30:33]
	v_mfma_f32_16x16x32_bf16 v[22:25], v[172:175], v[204:207], v[22:25]
	v_mfma_f32_16x16x32_bf16 v[14:17], v[180:183], v[204:207], v[14:17]
	v_mfma_f32_16x16x32_bf16 v[6:9], v[172:175], v[212:215], v[6:9]
	v_mfma_f32_16x16x32_bf16 v[2:5], v[180:183], v[212:215], v[2:5]
	s_setprio 0
	s_barrier
	s_add_i32 s69, s69, 2
	s_add_u32 s2, s2, 0x100
	s_addc_u32 s3, s3, 0
	s_add_u32 s67, s67, 0x100
	s_addc_u32 s68, s68, 0
	s_cmp_gt_u32 s69, 61
	s_cbranch_scc0 .LBB0_1521
	s_and_b64 vcc, exec, s[18:19]
	s_cbranch_vccz .LBB0_1524
	s_barrier

.LBB0_1697:
	ds_read_b128 v[130:133], v238
	ds_read_b128 v[134:137], v238 offset:1024
	ds_read_b128 v[138:141], v238 offset:2048
	ds_read_b128 v[142:145], v238 offset:3072
	ds_read_b128 v[146:149], v239
	ds_read_b128 v[150:153], v239 offset:1024
	ds_read_b128 v[154:157], v239 offset:2048
	ds_read_b128 v[158:161], v239 offset:3072
	s_add_u32 s56, s2, 0x100
	s_addc_u32 s57, s3, 0
	s_cmp_eq_u32 s91, 28
	s_cselect_b32 s61, s49, s57
	s_cselect_b32 s60, s87, s56
	s_cselect_b32 s59, s47, s90
	s_cselect_b32 s58, s88, s89
	s_add_i32 m0, s55, 0xc000
	ds_read_b128 v[162:165], v240
	ds_read_b128 v[166:169], v240 offset:1024
	ds_read_b128 v[170:173], v240 offset:2048
	ds_read_b128 v[174:177], v240 offset:3072
	ds_read_b128 v[178:181], v240 offset:4096
	ds_read_b128 v[182:185], v240 offset:5120
	ds_read_b128 v[186:189], v240 offset:6144
	ds_read_b128 v[190:193], v240 offset:7168
	global_load_lds_dwordx4 v210, s[2:3]
	s_add_i32 m0, s55, 0xe000
	s_nop 0
	global_load_lds_dwordx4 v212, s[2:3]
	s_waitcnt vmcnt(8)
	s_waitcnt lgkmcnt(0)
	s_barrier
	s_setprio 1
	s_waitcnt lgkmcnt(0)
	v_mfma_i32_16x16x64_i8 v[126:129], v[130:133], v[162:165], v[126:129]
	v_mfma_i32_16x16x64_i8 v[122:125], v[138:141], v[162:165], v[122:125]
	v_mfma_i32_16x16x64_i8 v[118:121], v[130:133], v[170:173], v[118:121]
	v_mfma_i32_16x16x64_i8 v[110:113], v[138:141], v[170:173], v[110:113]
	v_mfma_i32_16x16x64_i8 v[78:81], v[130:133], v[178:181], v[78:81]
	v_mfma_i32_16x16x64_i8 v[30:33], v[138:141], v[178:181], v[30:33]
	v_mfma_i32_16x16x64_i8 v[74:77], v[130:133], v[186:189], v[74:77]
	v_mfma_i32_16x16x64_i8 v[26:29], v[138:141], v[186:189], v[26:29]
	v_mfma_i32_16x16x64_i8 v[126:129], v[134:137], v[166:169], v[126:129]
	v_mfma_i32_16x16x64_i8 v[122:125], v[142:145], v[166:169], v[122:125]
	v_mfma_i32_16x16x64_i8 v[118:121], v[134:137], v[174:177], v[118:121]
	v_mfma_i32_16x16x64_i8 v[110:113], v[142:145], v[174:177], v[110:113]
	v_mfma_i32_16x16x64_i8 v[78:81], v[134:137], v[182:185], v[78:81]
	v_mfma_i32_16x16x64_i8 v[30:33], v[142:145], v[182:185], v[30:33]
	v_mfma_i32_16x16x64_i8 v[74:77], v[134:137], v[190:193], v[74:77]
	v_mfma_i32_16x16x64_i8 v[26:29], v[142:145], v[190:193], v[26:29]
	s_setprio 0
	s_setprio 1
	v_mfma_i32_16x16x64_i8 v[102:105], v[146:149], v[162:165], v[102:105]
	v_mfma_i32_16x16x64_i8 v[98:101], v[154:157], v[162:165], v[98:101]
	v_mfma_i32_16x16x64_i8 v[94:97], v[146:149], v[170:173], v[94:97]
	v_mfma_i32_16x16x64_i8 v[90:93], v[154:157], v[170:173], v[90:93]
	v_mfma_i32_16x16x64_i8 v[70:73], v[146:149], v[178:181], v[70:73]
	v_mfma_i32_16x16x64_i8 v[22:25], v[154:157], v[178:181], v[22:25]
	v_mfma_i32_16x16x64_i8 v[66:69], v[146:149], v[186:189], v[66:69]
	v_mfma_i32_16x16x64_i8 v[18:21], v[154:157], v[186:189], v[18:21]
	v_mfma_i32_16x16x64_i8 v[102:105], v[150:153], v[166:169], v[102:105]
	v_mfma_i32_16x16x64_i8 v[98:101], v[158:161], v[166:169], v[98:101]
	v_mfma_i32_16x16x64_i8 v[94:97], v[150:153], v[174:177], v[94:97]
	v_mfma_i32_16x16x64_i8 v[90:93], v[158:161], v[174:177], v[90:93]
	v_mfma_i32_16x16x64_i8 v[70:73], v[150:153], v[182:185], v[70:73]
	v_mfma_i32_16x16x64_i8 v[22:25], v[158:161], v[182:185], v[22:25]
	v_mfma_i32_16x16x64_i8 v[66:69], v[150:153], v[190:193], v[66:69]
	v_mfma_i32_16x16x64_i8 v[18:21], v[158:161], v[190:193], v[18:21]
	s_setprio 0
	s_barrier
	s_add_i32 s2, s83, s66
	s_add_u32 s98, s58, s36
	s_addc_u32 s99, s59, s37
	s_mov_b32 m0, s2
	ds_read_b128 v[162:165], v240 offset:16384
	ds_read_b128 v[166:169], v240 offset:17408
	ds_read_b128 v[170:173], v240 offset:18432
	ds_read_b128 v[174:177], v240 offset:19456
	ds_read_b128 v[178:181], v240 offset:20480
	ds_read_b128 v[182:185], v240 offset:21504
	ds_read_b128 v[186:189], v240 offset:22528
	ds_read_b128 v[190:193], v240 offset:23552
	global_load_lds_dwordx4 v206, s[58:59]
	s_add_i32 m0, s2, 0x2000
	s_add_u32 s2, s58, 0x80000
	s_addc_u32 s3, s59, 0
	s_add_i32 s43, s84, s66
	global_load_lds_dwordx4 v202, s[58:59]
	s_mov_b32 m0, s43
	s_nop 0
	global_load_lds_dwordx4 v206, s[2:3]
	s_add_i32 m0, s43, 0x2000
	s_nop 0
	global_load_lds_dwordx4 v202, s[2:3]
	s_add_u32 s100, s60, s36
	s_addc_u32 s101, s61, s37
	s_mov_b32 m0, s55
	s_nop 0
	global_load_lds_dwordx4 v208, s[60:61]
	s_mov_b32 m0, s68
	s_nop 0
	global_load_lds_dwordx4 v204, s[60:61]
	s_waitcnt vmcnt(8)
	s_waitcnt lgkmcnt(0)
	s_barrier
	s_setprio 1
	s_waitcnt lgkmcnt(0)
	v_mfma_i32_16x16x64_i8 v[62:65], v[130:133], v[162:165], v[62:65]
	v_mfma_i32_16x16x64_i8 v[14:17], v[138:141], v[162:165], v[14:17]
	v_mfma_i32_16x16x64_i8 v[58:61], v[130:133], v[170:173], v[58:61]
	v_mfma_i32_16x16x64_i8 v[10:13], v[138:141], v[170:173], v[10:13]
	v_mfma_i32_16x16x64_i8 v[114:117], v[130:133], v[178:181], v[114:117]
	v_mfma_i32_16x16x64_i8 v[106:109], v[138:141], v[178:181], v[106:109]
	v_mfma_i32_16x16x64_i8 v[86:89], v[130:133], v[186:189], v[86:89]
	v_mfma_i32_16x16x64_i8 v[82:85], v[138:141], v[186:189], v[82:85]
	v_mfma_i32_16x16x64_i8 v[62:65], v[134:137], v[166:169], v[62:65]
	v_mfma_i32_16x16x64_i8 v[14:17], v[142:145], v[166:169], v[14:17]
	v_mfma_i32_16x16x64_i8 v[58:61], v[134:137], v[174:177], v[58:61]
	v_mfma_i32_16x16x64_i8 v[10:13], v[142:145], v[174:177], v[10:13]
	v_mfma_i32_16x16x64_i8 v[114:117], v[134:137], v[182:185], v[114:117]
	v_mfma_i32_16x16x64_i8 v[106:109], v[142:145], v[182:185], v[106:109]
	v_mfma_i32_16x16x64_i8 v[86:89], v[134:137], v[190:193], v[86:89]
	v_mfma_i32_16x16x64_i8 v[82:85], v[142:145], v[190:193], v[82:85]
	s_setprio 0
	s_setprio 1
	v_mfma_i32_16x16x64_i8 v[50:53], v[146:149], v[162:165], v[50:53]
	v_mfma_i32_16x16x64_i8 v[6:9], v[154:157], v[162:165], v[6:9]
	v_mfma_i32_16x16x64_i8 v[42:45], v[146:149], v[170:173], v[42:45]
	v_mfma_i32_16x16x64_i8 v[2:5], v[154:157], v[170:173], v[2:5]
	v_mfma_i32_16x16x64_i8 v[54:57], v[146:149], v[178:181], v[54:57]
	v_mfma_i32_16x16x64_i8 v[46:49], v[154:157], v[178:181], v[46:49]
	v_mfma_i32_16x16x64_i8 v[38:41], v[146:149], v[186:189], v[38:41]
	v_mfma_i32_16x16x64_i8 v[34:37], v[154:157], v[186:189], v[34:37]
	v_mfma_i32_16x16x64_i8 v[50:53], v[150:153], v[166:169], v[50:53]
	v_mfma_i32_16x16x64_i8 v[6:9], v[158:161], v[166:169], v[6:9]
	v_mfma_i32_16x16x64_i8 v[42:45], v[150:153], v[174:177], v[42:45]
	v_mfma_i32_16x16x64_i8 v[2:5], v[158:161], v[174:177], v[2:5]
	v_mfma_i32_16x16x64_i8 v[54:57], v[150:153], v[182:185], v[54:57]
	v_mfma_i32_16x16x64_i8 v[46:49], v[158:161], v[182:185], v[46:49]
	v_mfma_i32_16x16x64_i8 v[38:41], v[150:153], v[190:193], v[38:41]
	v_mfma_i32_16x16x64_i8 v[34:37], v[158:161], v[190:193], v[34:37]
	s_setprio 0
	s_barrier
	s_add_i32 s43, 0, 0x18000
	s_add_i32 s92, 0, 0x1c000
	v_add_u32_e32 v142, s43, v237
	v_add_u32_e32 v158, s92, v237
	ds_read_b128 v[130:133], v142
	ds_read_b128 v[134:137], v142 offset:1024
	ds_read_b128 v[138:141], v142 offset:2048
	ds_read_b128 v[142:145], v142 offset:3072
	ds_read_b128 v[146:149], v158
	ds_read_b128 v[150:153], v158 offset:1024
	ds_read_b128 v[154:157], v158 offset:2048
	ds_read_b128 v[158:161], v158 offset:3072
	s_add_u32 s2, s60, 0x4000
	s_addc_u32 s3, s61, 0
	s_mov_b32 m0, s69
	ds_read_b128 v[162:165], v240 offset:32768
	ds_read_b128 v[166:169], v240 offset:33792
	ds_read_b128 v[170:173], v240 offset:34816
	ds_read_b128 v[174:177], v240 offset:35840
	ds_read_b128 v[178:181], v240 offset:36864
	ds_read_b128 v[182:185], v240 offset:37888
	ds_read_b128 v[186:189], v240 offset:38912
	ds_read_b128 v[190:193], v240 offset:39936
	global_load_lds_dwordx4 v208, s[2:3]
	s_mov_b32 m0, s70
	s_nop 0
	global_load_lds_dwordx4 v204, s[2:3]
	s_waitcnt vmcnt(8)
	s_waitcnt lgkmcnt(0)
	s_barrier
	s_setprio 1
	s_waitcnt lgkmcnt(0)
	v_mfma_i32_16x16x64_i8 v[126:129], v[130:133], v[162:165], v[126:129]
	v_mfma_i32_16x16x64_i8 v[122:125], v[138:141], v[162:165], v[122:125]
	v_mfma_i32_16x16x64_i8 v[118:121], v[130:133], v[170:173], v[118:121]
	v_mfma_i32_16x16x64_i8 v[110:113], v[138:141], v[170:173], v[110:113]
	v_mfma_i32_16x16x64_i8 v[78:81], v[130:133], v[178:181], v[78:81]
	v_mfma_i32_16x16x64_i8 v[30:33], v[138:141], v[178:181], v[30:33]
	v_mfma_i32_16x16x64_i8 v[74:77], v[130:133], v[186:189], v[74:77]
	v_mfma_i32_16x16x64_i8 v[26:29], v[138:141], v[186:189], v[26:29]
	v_mfma_i32_16x16x64_i8 v[126:129], v[134:137], v[166:169], v[126:129]
	v_mfma_i32_16x16x64_i8 v[122:125], v[142:145], v[166:169], v[122:125]
	v_mfma_i32_16x16x64_i8 v[118:121], v[134:137], v[174:177], v[118:121]
	v_mfma_i32_16x16x64_i8 v[110:113], v[142:145], v[174:177], v[110:113]
	v_mfma_i32_16x16x64_i8 v[78:81], v[134:137], v[182:185], v[78:81]
	v_mfma_i32_16x16x64_i8 v[30:33], v[142:145], v[182:185], v[30:33]
	v_mfma_i32_16x16x64_i8 v[74:77], v[134:137], v[190:193], v[74:77]
	v_mfma_i32_16x16x64_i8 v[26:29], v[142:145], v[190:193], v[26:29]
	s_setprio 0
	s_setprio 1
	v_mfma_i32_16x16x64_i8 v[102:105], v[146:149], v[162:165], v[102:105]
	v_mfma_i32_16x16x64_i8 v[98:101], v[154:157], v[162:165], v[98:101]
	v_mfma_i32_16x16x64_i8 v[94:97], v[146:149], v[170:173], v[94:97]
	v_mfma_i32_16x16x64_i8 v[90:93], v[154:157], v[170:173], v[90:93]
	v_mfma_i32_16x16x64_i8 v[70:73], v[146:149], v[178:181], v[70:73]
	v_mfma_i32_16x16x64_i8 v[22:25], v[154:157], v[178:181], v[22:25]
	v_mfma_i32_16x16x64_i8 v[66:69], v[146:149], v[186:189], v[66:69]
	v_mfma_i32_16x16x64_i8 v[18:21], v[154:157], v[186:189], v[18:21]
	v_mfma_i32_16x16x64_i8 v[102:105], v[150:153], v[166:169], v[102:105]
	v_mfma_i32_16x16x64_i8 v[98:101], v[158:161], v[166:169], v[98:101]
	v_mfma_i32_16x16x64_i8 v[94:97], v[150:153], v[174:177], v[94:97]
	v_mfma_i32_16x16x64_i8 v[90:93], v[158:161], v[174:177], v[90:93]
	v_mfma_i32_16x16x64_i8 v[70:73], v[150:153], v[182:185], v[70:73]
	v_mfma_i32_16x16x64_i8 v[22:25], v[158:161], v[182:185], v[22:25]
	v_mfma_i32_16x16x64_i8 v[66:69], v[150:153], v[190:193], v[66:69]
	v_mfma_i32_16x16x64_i8 v[18:21], v[158:161], v[190:193], v[18:21]
	s_setprio 0
	s_barrier
	s_add_i32 s2, s43, s66
	s_mov_b32 m0, s2
	ds_read_b128 v[162:165], v240 offset:49152
	ds_read_b128 v[166:169], v240 offset:50176
	ds_read_b128 v[170:173], v240 offset:51200
	ds_read_b128 v[174:177], v240 offset:52224
	ds_read_b128 v[178:181], v240 offset:53248
	ds_read_b128 v[182:185], v240 offset:54272
	ds_read_b128 v[186:189], v240 offset:55296
	ds_read_b128 v[190:193], v240 offset:56320
	global_load_lds_dwordx4 v206, s[98:99]
	s_add_i32 m0, s2, 0x2000
	s_add_u32 s2, s58, 0x80080
	s_addc_u32 s3, s59, 0
	s_add_i32 s43, s92, s66
	global_load_lds_dwordx4 v202, s[98:99]
	s_mov_b32 m0, s43
	s_nop 0
	global_load_lds_dwordx4 v206, s[2:3]
	s_add_i32 m0, s43, 0x2000
	s_nop 0
	global_load_lds_dwordx4 v202, s[2:3]
	s_mov_b32 m0, s77
	s_nop 0
	global_load_lds_dwordx4 v208, s[100:101]
	s_mov_b32 m0, s78
	s_nop 0
	global_load_lds_dwordx4 v204, s[100:101]
	s_waitcnt vmcnt(8)
	s_waitcnt lgkmcnt(0)
	s_barrier
	s_setprio 1
	s_waitcnt lgkmcnt(0)
	v_mfma_i32_16x16x64_i8 v[62:65], v[130:133], v[162:165], v[62:65]
	v_mfma_i32_16x16x64_i8 v[14:17], v[138:141], v[162:165], v[14:17]
	v_mfma_i32_16x16x64_i8 v[58:61], v[130:133], v[170:173], v[58:61]
	v_mfma_i32_16x16x64_i8 v[10:13], v[138:141], v[170:173], v[10:13]
	v_mfma_i32_16x16x64_i8 v[114:117], v[130:133], v[178:181], v[114:117]
	v_mfma_i32_16x16x64_i8 v[106:109], v[138:141], v[178:181], v[106:109]
	v_mfma_i32_16x16x64_i8 v[86:89], v[130:133], v[186:189], v[86:89]
	v_mfma_i32_16x16x64_i8 v[82:85], v[138:141], v[186:189], v[82:85]
	v_mfma_i32_16x16x64_i8 v[62:65], v[134:137], v[166:169], v[62:65]
	v_mfma_i32_16x16x64_i8 v[14:17], v[142:145], v[166:169], v[14:17]
	v_mfma_i32_16x16x64_i8 v[58:61], v[134:137], v[174:177], v[58:61]
	v_mfma_i32_16x16x64_i8 v[10:13], v[142:145], v[174:177], v[10:13]
	v_mfma_i32_16x16x64_i8 v[114:117], v[134:137], v[182:185], v[114:117]
	v_mfma_i32_16x16x64_i8 v[106:109], v[142:145], v[182:185], v[106:109]
	v_mfma_i32_16x16x64_i8 v[86:89], v[134:137], v[190:193], v[86:89]
	v_mfma_i32_16x16x64_i8 v[82:85], v[142:145], v[190:193], v[82:85]
	s_setprio 0
	s_setprio 1
	v_mfma_i32_16x16x64_i8 v[50:53], v[146:149], v[162:165], v[50:53]
	v_mfma_i32_16x16x64_i8 v[6:9], v[154:157], v[162:165], v[6:9]
	v_mfma_i32_16x16x64_i8 v[42:45], v[146:149], v[170:173], v[42:45]
	v_mfma_i32_16x16x64_i8 v[2:5], v[154:157], v[170:173], v[2:5]
	v_mfma_i32_16x16x64_i8 v[54:57], v[146:149], v[178:181], v[54:57]
	v_mfma_i32_16x16x64_i8 v[46:49], v[154:157], v[178:181], v[46:49]
	v_mfma_i32_16x16x64_i8 v[38:41], v[146:149], v[186:189], v[38:41]
	v_mfma_i32_16x16x64_i8 v[34:37], v[154:157], v[186:189], v[34:37]
	v_mfma_i32_16x16x64_i8 v[50:53], v[150:153], v[166:169], v[50:53]
	v_mfma_i32_16x16x64_i8 v[6:9], v[158:161], v[166:169], v[6:9]
	v_mfma_i32_16x16x64_i8 v[42:45], v[150:153], v[174:177], v[42:45]
	v_mfma_i32_16x16x64_i8 v[2:5], v[158:161], v[174:177], v[2:5]
	v_mfma_i32_16x16x64_i8 v[54:57], v[150:153], v[182:185], v[54:57]
	v_mfma_i32_16x16x64_i8 v[46:49], v[158:161], v[182:185], v[46:49]
	v_mfma_i32_16x16x64_i8 v[38:41], v[150:153], v[190:193], v[38:41]
	v_mfma_i32_16x16x64_i8 v[34:37], v[158:161], v[190:193], v[34:37]
	s_setprio 0
	s_barrier
	s_add_i32 s91, s91, 2
	s_add_u32 s89, s89, 0x100
	s_addc_u32 s90, s90, 0
	s_cmp_gt_u32 s91, 29
	s_mov_b64 s[2:3], s[56:57]
	s_cbranch_scc0 .LBB0_1697
	s_and_b64 vcc, exec, s[38:39]
	s_cbranch_vccz .LBB0_1700
	s_barrier

.LBB0_1951:
	ds_read_b128 v[130:133], v167
	ds_read_b128 v[134:137], v167 offset:1024
	ds_read_b128 v[138:141], v167 offset:2048
	ds_read_b128 v[142:145], v167 offset:3072
	ds_read_b128 v[170:173], v168
	ds_read_b128 v[174:177], v168 offset:1024
	ds_read_b128 v[178:181], v168 offset:2048
	ds_read_b128 v[182:185], v168 offset:3072
	s_add_u32 s38, s36, 0x100
	s_addc_u32 s39, s37, 0
	s_cmpk_eq_i32 s77, 0x52
	s_cselect_b32 s47, s3, s39
	s_cselect_b32 s46, s2, s38
	s_cselect_b32 s45, s35, s76
	s_cselect_b32 s44, s34, s75
	s_add_i32 m0, s52, 0xc000
	ds_read_b128 v[186:189], v169
	ds_read_b128 v[190:193], v169 offset:1024
	ds_read_b128 v[194:197], v169 offset:2048
	ds_read_b128 v[198:201], v169 offset:3072
	ds_read_b128 v[202:205], v169 offset:4096
	ds_read_b128 v[206:209], v169 offset:5120
	ds_read_b128 v[210:213], v169 offset:6144
	ds_read_b128 v[214:217], v169 offset:7168
	global_load_lds_dwordx4 v154, s[36:37]
	s_add_i32 m0, s52, 0xe000
	s_nop 0
	global_load_lds_dwordx4 v156, s[36:37]
	s_waitcnt vmcnt(8)
	s_waitcnt lgkmcnt(0)
	s_barrier
	s_setprio 1
	s_waitcnt lgkmcnt(0)
	v_mfma_i32_16x16x64_i8 v[126:129], v[130:133], v[186:189], v[126:129]
	v_mfma_i32_16x16x64_i8 v[122:125], v[138:141], v[186:189], v[122:125]
	v_mfma_i32_16x16x64_i8 v[110:113], v[130:133], v[194:197], v[110:113]
	v_mfma_i32_16x16x64_i8 v[106:109], v[138:141], v[194:197], v[106:109]
	v_mfma_i32_16x16x64_i8 v[94:97], v[130:133], v[202:205], v[94:97]
	v_mfma_i32_16x16x64_i8 v[90:93], v[138:141], v[202:205], v[90:93]
	v_mfma_i32_16x16x64_i8 v[78:81], v[130:133], v[210:213], v[78:81]
	v_mfma_i32_16x16x64_i8 v[74:77], v[138:141], v[210:213], v[74:77]
	v_mfma_i32_16x16x64_i8 v[126:129], v[134:137], v[190:193], v[126:129]
	v_mfma_i32_16x16x64_i8 v[122:125], v[142:145], v[190:193], v[122:125]
	v_mfma_i32_16x16x64_i8 v[110:113], v[134:137], v[198:201], v[110:113]
	v_mfma_i32_16x16x64_i8 v[106:109], v[142:145], v[198:201], v[106:109]
	v_mfma_i32_16x16x64_i8 v[94:97], v[134:137], v[206:209], v[94:97]
	v_mfma_i32_16x16x64_i8 v[90:93], v[142:145], v[206:209], v[90:93]
	v_mfma_i32_16x16x64_i8 v[78:81], v[134:137], v[214:217], v[78:81]
	v_mfma_i32_16x16x64_i8 v[74:77], v[142:145], v[214:217], v[74:77]
	s_setprio 0
	s_setprio 1
	v_mfma_i32_16x16x64_i8 v[118:121], v[170:173], v[186:189], v[118:121]
	v_mfma_i32_16x16x64_i8 v[114:117], v[178:181], v[186:189], v[114:117]
	v_mfma_i32_16x16x64_i8 v[102:105], v[170:173], v[194:197], v[102:105]
	v_mfma_i32_16x16x64_i8 v[98:101], v[178:181], v[194:197], v[98:101]
	v_mfma_i32_16x16x64_i8 v[86:89], v[170:173], v[202:205], v[86:89]
	v_mfma_i32_16x16x64_i8 v[82:85], v[178:181], v[202:205], v[82:85]
	v_mfma_i32_16x16x64_i8 v[70:73], v[170:173], v[210:213], v[70:73]
	v_mfma_i32_16x16x64_i8 v[66:69], v[178:181], v[210:213], v[66:69]
	v_mfma_i32_16x16x64_i8 v[118:121], v[174:177], v[190:193], v[118:121]
	v_mfma_i32_16x16x64_i8 v[114:117], v[182:185], v[190:193], v[114:117]
	v_mfma_i32_16x16x64_i8 v[102:105], v[174:177], v[198:201], v[102:105]
	v_mfma_i32_16x16x64_i8 v[98:101], v[182:185], v[198:201], v[98:101]
	v_mfma_i32_16x16x64_i8 v[86:89], v[174:177], v[206:209], v[86:89]
	v_mfma_i32_16x16x64_i8 v[82:85], v[182:185], v[206:209], v[82:85]
	v_mfma_i32_16x16x64_i8 v[70:73], v[174:177], v[214:217], v[70:73]
	v_mfma_i32_16x16x64_i8 v[66:69], v[182:185], v[214:217], v[66:69]
	s_setprio 0
	s_barrier
	s_add_i32 s36, s61, s51
	s_add_u32 s98, s44, s14
	s_addc_u32 s99, s45, s15
	s_mov_b32 m0, s36
	ds_read_b128 v[186:189], v169 offset:16384
	ds_read_b128 v[190:193], v169 offset:17408
	ds_read_b128 v[194:197], v169 offset:18432
	ds_read_b128 v[198:201], v169 offset:19456
	ds_read_b128 v[202:205], v169 offset:20480
	ds_read_b128 v[206:209], v169 offset:21504
	ds_read_b128 v[210:213], v169 offset:22528
	ds_read_b128 v[214:217], v169 offset:23552
	global_load_lds_dwordx4 v150, s[44:45]
	s_add_i32 m0, s36, 0x2000
	s_add_u32 s36, s44, 0x158000
	s_addc_u32 s37, s45, 0
	s_add_i32 s78, s62, s51
	global_load_lds_dwordx4 v146, s[44:45]
	s_mov_b32 m0, s78
	s_nop 0
	global_load_lds_dwordx4 v150, s[36:37]
	s_add_i32 m0, s78, 0x2000
	s_nop 0
	global_load_lds_dwordx4 v146, s[36:37]
	s_add_u32 s100, s46, s14
	s_addc_u32 s101, s47, s15
	s_mov_b32 m0, s52
	s_nop 0
	global_load_lds_dwordx4 v152, s[46:47]
	s_mov_b32 m0, s53
	s_nop 0
	global_load_lds_dwordx4 v148, s[46:47]
	s_waitcnt vmcnt(8)
	s_waitcnt lgkmcnt(0)
	s_barrier
	s_setprio 1
	s_waitcnt lgkmcnt(0)
	v_mfma_i32_16x16x64_i8 v[62:65], v[130:133], v[186:189], v[62:65]
	v_mfma_i32_16x16x64_i8 v[58:61], v[138:141], v[186:189], v[58:61]
	v_mfma_i32_16x16x64_i8 v[46:49], v[130:133], v[194:197], v[46:49]
	v_mfma_i32_16x16x64_i8 v[42:45], v[138:141], v[194:197], v[42:45]
	v_mfma_i32_16x16x64_i8 v[30:33], v[130:133], v[202:205], v[30:33]
	v_mfma_i32_16x16x64_i8 v[26:29], v[138:141], v[202:205], v[26:29]
	v_mfma_i32_16x16x64_i8 v[14:17], v[130:133], v[210:213], v[14:17]
	v_mfma_i32_16x16x64_i8 v[10:13], v[138:141], v[210:213], v[10:13]
	v_mfma_i32_16x16x64_i8 v[62:65], v[134:137], v[190:193], v[62:65]
	v_mfma_i32_16x16x64_i8 v[58:61], v[142:145], v[190:193], v[58:61]
	v_mfma_i32_16x16x64_i8 v[46:49], v[134:137], v[198:201], v[46:49]
	v_mfma_i32_16x16x64_i8 v[42:45], v[142:145], v[198:201], v[42:45]
	v_mfma_i32_16x16x64_i8 v[30:33], v[134:137], v[206:209], v[30:33]
	v_mfma_i32_16x16x64_i8 v[26:29], v[142:145], v[206:209], v[26:29]
	v_mfma_i32_16x16x64_i8 v[14:17], v[134:137], v[214:217], v[14:17]
	v_mfma_i32_16x16x64_i8 v[10:13], v[142:145], v[214:217], v[10:13]
	s_setprio 0
	s_setprio 1
	v_mfma_i32_16x16x64_i8 v[54:57], v[170:173], v[186:189], v[54:57]
	v_mfma_i32_16x16x64_i8 v[50:53], v[178:181], v[186:189], v[50:53]
	v_mfma_i32_16x16x64_i8 v[38:41], v[170:173], v[194:197], v[38:41]
	v_mfma_i32_16x16x64_i8 v[34:37], v[178:181], v[194:197], v[34:37]
	v_mfma_i32_16x16x64_i8 v[22:25], v[170:173], v[202:205], v[22:25]
	v_mfma_i32_16x16x64_i8 v[18:21], v[178:181], v[202:205], v[18:21]
	v_mfma_i32_16x16x64_i8 v[6:9], v[170:173], v[210:213], v[6:9]
	v_mfma_i32_16x16x64_i8 v[2:5], v[178:181], v[210:213], v[2:5]
	v_mfma_i32_16x16x64_i8 v[54:57], v[174:177], v[190:193], v[54:57]
	v_mfma_i32_16x16x64_i8 v[50:53], v[182:185], v[190:193], v[50:53]
	v_mfma_i32_16x16x64_i8 v[38:41], v[174:177], v[198:201], v[38:41]
	v_mfma_i32_16x16x64_i8 v[34:37], v[182:185], v[198:201], v[34:37]
	v_mfma_i32_16x16x64_i8 v[22:25], v[174:177], v[206:209], v[22:25]
	v_mfma_i32_16x16x64_i8 v[18:21], v[182:185], v[206:209], v[18:21]
	v_mfma_i32_16x16x64_i8 v[6:9], v[174:177], v[214:217], v[6:9]
	v_mfma_i32_16x16x64_i8 v[2:5], v[182:185], v[214:217], v[2:5]
	s_setprio 0
	s_barrier
	s_add_i32 s78, 0, 0x18000
	s_add_i32 s79, 0, 0x1c000
	v_add_u32_e32 v142, s78, v166
	v_add_u32_e32 v182, s79, v166
	ds_read_b128 v[130:133], v142
	ds_read_b128 v[134:137], v142 offset:1024
	ds_read_b128 v[138:141], v142 offset:2048
	ds_read_b128 v[142:145], v142 offset:3072
	ds_read_b128 v[170:173], v182
	ds_read_b128 v[174:177], v182 offset:1024
	ds_read_b128 v[178:181], v182 offset:2048
	ds_read_b128 v[182:185], v182 offset:3072
	s_add_u32 s36, s46, 0x158000
	s_addc_u32 s37, s47, 0
	s_mov_b32 m0, s54
	ds_read_b128 v[186:189], v169 offset:32768
	ds_read_b128 v[190:193], v169 offset:33792
	ds_read_b128 v[194:197], v169 offset:34816
	ds_read_b128 v[198:201], v169 offset:35840
	ds_read_b128 v[202:205], v169 offset:36864
	ds_read_b128 v[206:209], v169 offset:37888
	ds_read_b128 v[210:213], v169 offset:38912
	ds_read_b128 v[214:217], v169 offset:39936
	global_load_lds_dwordx4 v152, s[36:37]
	s_mov_b32 m0, s55
	s_nop 0
	global_load_lds_dwordx4 v148, s[36:37]
	s_waitcnt vmcnt(8)
	s_waitcnt lgkmcnt(0)
	s_barrier
	s_setprio 1
	s_waitcnt lgkmcnt(0)
	v_mfma_i32_16x16x64_i8 v[126:129], v[130:133], v[186:189], v[126:129]
	v_mfma_i32_16x16x64_i8 v[122:125], v[138:141], v[186:189], v[122:125]
	v_mfma_i32_16x16x64_i8 v[110:113], v[130:133], v[194:197], v[110:113]
	v_mfma_i32_16x16x64_i8 v[106:109], v[138:141], v[194:197], v[106:109]
	v_mfma_i32_16x16x64_i8 v[94:97], v[130:133], v[202:205], v[94:97]
	v_mfma_i32_16x16x64_i8 v[90:93], v[138:141], v[202:205], v[90:93]
	v_mfma_i32_16x16x64_i8 v[78:81], v[130:133], v[210:213], v[78:81]
	v_mfma_i32_16x16x64_i8 v[74:77], v[138:141], v[210:213], v[74:77]
	v_mfma_i32_16x16x64_i8 v[126:129], v[134:137], v[190:193], v[126:129]
	v_mfma_i32_16x16x64_i8 v[122:125], v[142:145], v[190:193], v[122:125]
	v_mfma_i32_16x16x64_i8 v[110:113], v[134:137], v[198:201], v[110:113]
	v_mfma_i32_16x16x64_i8 v[106:109], v[142:145], v[198:201], v[106:109]
	v_mfma_i32_16x16x64_i8 v[94:97], v[134:137], v[206:209], v[94:97]
	v_mfma_i32_16x16x64_i8 v[90:93], v[142:145], v[206:209], v[90:93]
	v_mfma_i32_16x16x64_i8 v[78:81], v[134:137], v[214:217], v[78:81]
	v_mfma_i32_16x16x64_i8 v[74:77], v[142:145], v[214:217], v[74:77]
	s_setprio 0
	s_setprio 1
	v_mfma_i32_16x16x64_i8 v[118:121], v[170:173], v[186:189], v[118:121]
	v_mfma_i32_16x16x64_i8 v[114:117], v[178:181], v[186:189], v[114:117]
	v_mfma_i32_16x16x64_i8 v[102:105], v[170:173], v[194:197], v[102:105]
	v_mfma_i32_16x16x64_i8 v[98:101], v[178:181], v[194:197], v[98:101]
	v_mfma_i32_16x16x64_i8 v[86:89], v[170:173], v[202:205], v[86:89]
	v_mfma_i32_16x16x64_i8 v[82:85], v[178:181], v[202:205], v[82:85]
	v_mfma_i32_16x16x64_i8 v[70:73], v[170:173], v[210:213], v[70:73]
	v_mfma_i32_16x16x64_i8 v[66:69], v[178:181], v[210:213], v[66:69]
	v_mfma_i32_16x16x64_i8 v[118:121], v[174:177], v[190:193], v[118:121]
	v_mfma_i32_16x16x64_i8 v[114:117], v[182:185], v[190:193], v[114:117]
	v_mfma_i32_16x16x64_i8 v[102:105], v[174:177], v[198:201], v[102:105]
	v_mfma_i32_16x16x64_i8 v[98:101], v[182:185], v[198:201], v[98:101]
	v_mfma_i32_16x16x64_i8 v[86:89], v[174:177], v[206:209], v[86:89]
	v_mfma_i32_16x16x64_i8 v[82:85], v[182:185], v[206:209], v[82:85]
	v_mfma_i32_16x16x64_i8 v[70:73], v[174:177], v[214:217], v[70:73]
	v_mfma_i32_16x16x64_i8 v[66:69], v[182:185], v[214:217], v[66:69]
	s_setprio 0
	s_barrier
	s_add_i32 s36, s78, s51
	s_mov_b32 m0, s36
	ds_read_b128 v[186:189], v169 offset:49152
	ds_read_b128 v[190:193], v169 offset:50176
	ds_read_b128 v[194:197], v169 offset:51200
	ds_read_b128 v[198:201], v169 offset:52224
	ds_read_b128 v[202:205], v169 offset:53248
	ds_read_b128 v[206:209], v169 offset:54272
	ds_read_b128 v[210:213], v169 offset:55296
	ds_read_b128 v[214:217], v169 offset:56320
	global_load_lds_dwordx4 v150, s[98:99]
	s_add_i32 m0, s36, 0x2000
	s_add_u32 s36, s44, 0x158080
	s_addc_u32 s37, s45, 0
	s_add_i32 s44, s79, s51
	global_load_lds_dwordx4 v146, s[98:99]
	s_mov_b32 m0, s44
	s_nop 0
	global_load_lds_dwordx4 v150, s[36:37]
	s_add_i32 m0, s44, 0x2000
	s_nop 0
	global_load_lds_dwordx4 v146, s[36:37]
	s_mov_b32 m0, s59
	s_nop 0
	global_load_lds_dwordx4 v152, s[100:101]
	s_mov_b32 m0, s60
	s_nop 0
	global_load_lds_dwordx4 v148, s[100:101]
	s_waitcnt vmcnt(8)
	s_waitcnt lgkmcnt(0)
	s_barrier
	s_setprio 1
	s_waitcnt lgkmcnt(0)
	v_mfma_i32_16x16x64_i8 v[62:65], v[130:133], v[186:189], v[62:65]
	v_mfma_i32_16x16x64_i8 v[58:61], v[138:141], v[186:189], v[58:61]
	v_mfma_i32_16x16x64_i8 v[46:49], v[130:133], v[194:197], v[46:49]
	v_mfma_i32_16x16x64_i8 v[42:45], v[138:141], v[194:197], v[42:45]
	v_mfma_i32_16x16x64_i8 v[30:33], v[130:133], v[202:205], v[30:33]
	v_mfma_i32_16x16x64_i8 v[26:29], v[138:141], v[202:205], v[26:29]
	v_mfma_i32_16x16x64_i8 v[14:17], v[130:133], v[210:213], v[14:17]
	v_mfma_i32_16x16x64_i8 v[10:13], v[138:141], v[210:213], v[10:13]
	v_mfma_i32_16x16x64_i8 v[62:65], v[134:137], v[190:193], v[62:65]
	v_mfma_i32_16x16x64_i8 v[58:61], v[142:145], v[190:193], v[58:61]
	v_mfma_i32_16x16x64_i8 v[46:49], v[134:137], v[198:201], v[46:49]
	v_mfma_i32_16x16x64_i8 v[42:45], v[142:145], v[198:201], v[42:45]
	v_mfma_i32_16x16x64_i8 v[30:33], v[134:137], v[206:209], v[30:33]
	v_mfma_i32_16x16x64_i8 v[26:29], v[142:145], v[206:209], v[26:29]
	v_mfma_i32_16x16x64_i8 v[14:17], v[134:137], v[214:217], v[14:17]
	v_mfma_i32_16x16x64_i8 v[10:13], v[142:145], v[214:217], v[10:13]
	s_setprio 0
	s_setprio 1
	v_mfma_i32_16x16x64_i8 v[54:57], v[170:173], v[186:189], v[54:57]
	v_mfma_i32_16x16x64_i8 v[50:53], v[178:181], v[186:189], v[50:53]
	v_mfma_i32_16x16x64_i8 v[38:41], v[170:173], v[194:197], v[38:41]
	v_mfma_i32_16x16x64_i8 v[34:37], v[178:181], v[194:197], v[34:37]
	v_mfma_i32_16x16x64_i8 v[22:25], v[170:173], v[202:205], v[22:25]
	v_mfma_i32_16x16x64_i8 v[18:21], v[178:181], v[202:205], v[18:21]
	v_mfma_i32_16x16x64_i8 v[6:9], v[170:173], v[210:213], v[6:9]
	v_mfma_i32_16x16x64_i8 v[2:5], v[178:181], v[210:213], v[2:5]
	v_mfma_i32_16x16x64_i8 v[54:57], v[174:177], v[190:193], v[54:57]
	v_mfma_i32_16x16x64_i8 v[50:53], v[182:185], v[190:193], v[50:53]
	v_mfma_i32_16x16x64_i8 v[38:41], v[174:177], v[198:201], v[38:41]
	v_mfma_i32_16x16x64_i8 v[34:37], v[182:185], v[198:201], v[34:37]
	v_mfma_i32_16x16x64_i8 v[22:25], v[174:177], v[206:209], v[22:25]
	v_mfma_i32_16x16x64_i8 v[18:21], v[182:185], v[206:209], v[18:21]
	v_mfma_i32_16x16x64_i8 v[6:9], v[174:177], v[214:217], v[6:9]
	v_mfma_i32_16x16x64_i8 v[2:5], v[182:185], v[214:217], v[2:5]
	s_setprio 0
	s_barrier
	s_add_i32 s77, s77, 2
	s_add_u32 s75, s75, 0x100
	s_addc_u32 s76, s76, 0
	s_cmpk_gt_u32 s77, 0x53
	s_mov_b64 s[36:37], s[38:39]
	s_cbranch_scc0 .LBB0_1951
	s_and_b64 vcc, exec, s[16:17]
	s_cbranch_vccz .LBB0_1954
	s_barrier

	.amdhsa_kernel _Z3fwd4Args
		.amdhsa_group_segment_fixed_size 0
		.amdhsa_private_segment_fixed_size 0
		.amdhsa_kernarg_size 464
		.amdhsa_user_sgpr_count 2
		.amdhsa_user_sgpr_dispatch_ptr 0
		.amdhsa_user_sgpr_queue_ptr 0
		.amdhsa_user_sgpr_kernarg_segment_ptr 1
		.amdhsa_user_sgpr_dispatch_id 0
		.amdhsa_user_sgpr_kernarg_preload_length 0
		.amdhsa_user_sgpr_kernarg_preload_offset 0
		.amdhsa_user_sgpr_private_segment_size 0
		.amdhsa_uses_dynamic_stack 0
		.amdhsa_enable_private_segment 0
		.amdhsa_system_sgpr_workgroup_id_x 1
		.amdhsa_system_sgpr_workgroup_id_y 0
		.amdhsa_system_sgpr_workgroup_id_z 0
		.amdhsa_system_sgpr_workgroup_info 0
		.amdhsa_system_vgpr_workitem_id 0
		.amdhsa_next_free_vgpr 253
		.amdhsa_next_free_sgpr 102
		.amdhsa_accum_offset 256
		.amdhsa_reserve_vcc 1
		.amdhsa_float_round_mode_32 0
		.amdhsa_float_round_mode_16_64 0
		.amdhsa_float_denorm_mode_32 3
		.amdhsa_float_denorm_mode_16_64 3
		.amdhsa_dx10_clamp 1
		.amdhsa_ieee_mode 1
		.amdhsa_fp16_overflow 0
		.amdhsa_tg_split 0
		.amdhsa_exception_fp_ieee_invalid_op 0
		.amdhsa_exception_fp_denorm_src 0
		.amdhsa_exception_fp_ieee_div_zero 0
		.amdhsa_exception_fp_ieee_overflow 0
		.amdhsa_exception_fp_ieee_underflow 0
		.amdhsa_exception_fp_ieee_inexact 0
		.amdhsa_exception_int_div_zero 0
	.end_amdhsa_kernel

amdhsa.kernels:
  - .agpr_count:     0
    .args:
      - .offset:         0
        .size:           208
        .value_kind:     by_value
      - .offset:         208
        .size:           4
        .value_kind:     hidden_block_count_x
      - .offset:         212
        .size:           4
        .value_kind:     hidden_block_count_y
      - .offset:         216
        .size:           4
        .value_kind:     hidden_block_count_z
      - .offset:         220
        .size:           2
        .value_kind:     hidden_group_size_x
      - .offset:         222
        .size:           2
        .value_kind:     hidden_group_size_y
      - .offset:         224
        .size:           2
        .value_kind:     hidden_group_size_z
      - .offset:         226
        .size:           2
        .value_kind:     hidden_remainder_x
      - .offset:         228
        .size:           2
        .value_kind:     hidden_remainder_y
      - .offset:         230
        .size:           2
        .value_kind:     hidden_remainder_z
      - .offset:         248
        .size:           8
        .value_kind:     hidden_global_offset_x
      - .offset:         256
        .size:           8
        .value_kind:     hidden_global_offset_y
      - .offset:         264
        .size:           8
        .value_kind:     hidden_global_offset_z
      - .offset:         272
        .size:           2
        .value_kind:     hidden_grid_dims
      - .offset:         328
        .size:           4
        .value_kind:     hidden_dynamic_lds_size
    .group_segment_fixed_size: 0
    .kernarg_segment_align: 8
    .kernarg_segment_size: 464
    .language:       OpenCL C
    .language_version:
      - 2
      - 0
    .max_flat_workgroup_size: 512
    .name:           _Z3fwd4Args
    .private_segment_fixed_size: 0
    .sgpr_count:     108
    .sgpr_spill_count: 186
    .symbol:         _Z3fwd4Args.kd
    .uniform_work_group_size: 1
    .uses_dynamic_stack: false
    .vgpr_count:     253
    .vgpr_spill_count: 0
    .wavefront_size: 64
